# hot loop heads (GEMM, attention, mixer loops) aligned to 64 bytes; on top of v50
# speedup vs baseline: 1.0037x; 1.0037x over previous
;     ...
; #pragma unroll 1
;     for (int s = 0; s < S; s += 2) {
;       issue(ra0, rb0, rx0);
;       compute(0);
;       store(ra1, rb1, rx1, 1);
;       __syncthreads();
;       issue(ra1, rb1, rx1);
;       compute(1);
;       c_kt += 2;
;       if (c_kt == nk) { c_kt = 0; tile_end(); }
;       store(ra0, rb0, rx0, 0);
;       __syncthreads();
;     }
.LBB0_588:
	s_load_dwordx2 s[4:5], s[0:1], 0x110
	s_add_i32 s36, s36, 1
	s_cmp_eq_u32 s36, 16
	s_cselect_b32 s6, 0, s36
	s_waitcnt lgkmcnt(0)
	s_cselect_b32 s4, s4, 0
	s_add_i32 s7, s4, s34
	s_add_i32 s56, s56, 2
	s_cmp_lt_i32 s56, s55
	s_barrier
	s_cbranch_scc0 .LBB0_636
	.p2align 6

;     ...
; #pragma unroll 1
;     for (int s = 0; s < S; s += 2) {
;       issue(ra0, rb0, rx0);
;       compute(0);
;       store(ra1, rb1, rx1, 1);
;       __syncthreads();
;       issue(ra1, rb1, rx1);
;       compute(1);
;       c_kt += 2;
;       if (c_kt == nk) { c_kt = 0; tile_end(); }
;       store(ra0, rb0, rx0, 0);
;       __syncthreads();
;     }
.LBB0_697:
	s_load_dwordx2 s[12:13], s[0:1], 0x110
	s_add_i32 s44, s44, 1
	s_cmp_eq_u32 s44, 8
	s_cselect_b32 s10, 0, s44
	s_waitcnt lgkmcnt(0)
	s_cselect_b32 s11, s12, 0
	s_add_i32 s11, s11, s46
	s_add_i32 s9, s9, 2
	s_cmp_lt_i32 s9, s8
	s_barrier
	s_cbranch_scc0 .LBB0_733
	.p2align 6

;     ...
; #pragma unroll 1
;     for (int s = 0; s < S; s += 2) {
;       issue(ra0, rb0, rx0);
;       compute(0);
;       store(ra1, rb1, rx1, 1);
;       __syncthreads();
;       issue(ra1, rb1, rx1);
;       compute(1);
;       c_kt += 2;
;       if (c_kt == nk) { c_kt = 0; tile_end(); }
;       store(ra0, rb0, rx0, 0);
;       __syncthreads();
;     }
.LBB0_745:
	s_load_dwordx2 s[4:5], s[0:1], 0x110
	s_add_i32 s6, s6, 1
	s_cmp_eq_u32 s6, 4
	s_cselect_b32 s6, 0, s6
	s_waitcnt lgkmcnt(0)
	s_cselect_b32 s4, s4, 0
	s_add_i32 s7, s4, s8
	s_add_i32 s34, s34, 2
	s_cmp_le_i32 s34, s31
	s_barrier
	s_cbranch_scc0 .LBB0_785
	.p2align 6

; __device__ __forceinline__ void attn_unit(const WS& ws, int u, bool dry = false) {
;     ...
;       const u32x4 raw = *(const u32x4*)(ws.QB + (size_t)(b * T_ + qc) * 1536 + hd * 96 + 64 + 8 * lq);
;       u32x4 oth;
;       oth.x = __shfl_xor(raw.x, 32); oth.y = __shfl_xor(raw.y, 32); oth.z = __shfl_xor(raw.z, 32); oth.w = __shfl_xor(raw.w, 32);
;       const float sgn = lq < 2 ? -1.f : 1.f;
;       const float2* rp = ws.ROPE + (size_t)(b * T_ + qc) * 16 + 8 * (lq & 1);
;       const unsigned rw[4] = {raw.x, raw.y, raw.z, raw.w}, ow[4] = {oth.x, oth.y, oth.z, oth.w};
;       unsigned res[4];
; #pragma unroll
;       for (int e = 0; e < 4; ++e) {
;         const float2 c0 = rp[2 * e], c1 = rp[2 * e + 1];
;         const float r0 = bflo(rw[e]) * c0.x + sgn * bflo(ow[e]) * c0.y;
;         const float r1 = bfhi(rw[e]) * c1.x + sgn * bfhi(ow[e]) * c1.y;
;         res[e] = cvt_pk_bf16(r0, r1);
;       }
;       xq[nt][2] = as_bf16x8((u32x4){res[0], res[1], res[2], res[3]});
;     }
;   }
;   float mrun[2] = {-INFINITY, -INFINITY}, lsum[2] = {0.f, 0.f};
;   f32x4 oacc[4][2];
; #pragma unroll
;   for (int a = 0; a < 4; ++a)
; #pragma unroll
;     for (int bb = 0; bb < 2; ++bb) oacc[a][bb] = (f32x4){0.f, 0.f, 0.f, 0.f};
;   u32x4 kregA[3], vregA[2], kregB[3], vregB[2];
;   const bf16_t* vbase = ws.VT + ((size_t)(b * 16 + hd) * 64) * TP_;
;   auto loadg = [&](int kt, u32x4 (&kreg)[3], u32x4 (&vreg)[2]) {
; #pragma unroll
;     for (int i = 0; i < 3; ++i) {
;       const int ci = tid + 256 * i; const int key = ci / 12, ch = ci - key * 12;
;       int gk = 64 * kt + key; if (gk > T_ - 1) gk = T_ - 1;
;       const bf16_t* src = ch < 8 ? ws.KN + (size_t)(b * T_ + gk) * 1024 + hd * 64 + ch * 8
;                                  : ws.KR + (size_t)(b * T_ + gk) * 32 + (ch - 8) * 8;
;       kreg[i] = *(const u32x4*)src;
;     }
; #pragma unroll
;     for (int i = 0; i < 2; ++i) {
;       const int ci = tid + 256 * i; const int dv = ci >> 3, ch = ci & 7;
;       vreg[i] = *(const u32x4*)(vbase + (size_t)dv * TP_ + 64 * kt + ch * 8);
;       if (64 * kt + ch * 8 >= T_) vreg[i] = (u32x4){0u, 0u, 0u, 0u};
;     }
;   };
;   auto stores = [&](int buf, const u32x4 (&kreg)[3], const u32x4 (&vreg)[2]) {
; #pragma unroll
;     for (int i = 0; i < 3; ++i) {
;       const int ci = tid + 256 * i; const int key = ci / 12, ch = ci - key * 12;
.LBB0_862:
	s_or_b64 exec, exec, s[4:5]
	v_cmp_gt_u32_e32 vcc, 2, v109
	v_lshlrev_b32_e32 v122, 16, v22
	v_and_b32_e32 v125, 0xffff0000, v22
	v_cndmask_b32_e64 v107, 1.0, -1.0, vcc
	s_waitcnt lgkmcnt(7)
	v_and_b32_e32 v22, 0xffff0000, v115
	v_mov_b32_e32 v72, v67
	v_mov_b32_e32 v118, v55
	v_lshlrev_b32_e32 v55, 16, v115
	v_mul_f32_e32 v123, v107, v22
	v_mov_b32_e32 v67, v69
	v_mov_b32_e32 v73, v68
	v_mul_f32_e32 v124, v107, v55
	v_pk_mul_f32 v[66:67], v[66:67], v[122:123]
	v_and_b32_e32 v69, 0xffff0000, v23
	v_pk_fma_f32 v[66:67], v[124:125], v[72:73], v[66:67]
	v_mov_b32_e32 v78, v63
	v_cvt_pk_bf16_f32 v22, v66, v67
	v_lshlrev_b32_e32 v66, 16, v23
	s_waitcnt lgkmcnt(6)
	v_and_b32_e32 v23, 0xffff0000, v114
	v_lshlrev_b32_e32 v55, 16, v114
	v_mul_f32_e32 v67, v107, v23
	v_mov_b32_e32 v63, v65
	v_mov_b32_e32 v79, v64
	v_mul_f32_e32 v68, v107, v55
	v_pk_mul_f32 v[62:63], v[62:63], v[66:67]
	s_waitcnt lgkmcnt(5)
	v_lshlrev_b32_e32 v55, 16, v113
	v_pk_fma_f32 v[62:63], v[68:69], v[78:79], v[62:63]
	v_and_b32_e32 v65, 0xffff0000, v24
	v_cvt_pk_bf16_f32 v23, v62, v63
	v_lshlrev_b32_e32 v62, 16, v24
	v_and_b32_e32 v24, 0xffff0000, v113
	v_mul_f32_e32 v64, v107, v55
	v_mul_f32_e32 v63, v107, v24
	v_mov_b32_e32 v55, v57
	v_mov_b32_e32 v119, v56
	v_pk_mul_f32 v[54:55], v[54:55], v[62:63]
	v_and_b32_e32 v57, 0xffff0000, v25
	v_pk_fma_f32 v[54:55], v[64:65], v[118:119], v[54:55]
	s_waitcnt vmcnt(12)
	v_mov_b32_e32 v120, v59
	v_cvt_pk_bf16_f32 v24, v54, v55
	v_lshlrev_b32_e32 v54, 16, v25
	s_waitcnt lgkmcnt(4)
	v_lshlrev_b32_e32 v55, 16, v112
	v_and_b32_e32 v25, 0xffff0000, v112
	v_mul_f32_e32 v56, v107, v55
	v_mul_f32_e32 v55, v107, v25
	v_mov_b32_e32 v59, v61
	v_mov_b32_e32 v121, v60
	v_pk_mul_f32 v[54:55], v[58:59], v[54:55]
	v_lshlrev_b32_e32 v62, 16, v30
	v_pk_fma_f32 v[54:55], v[56:57], v[120:121], v[54:55]
	v_and_b32_e32 v65, 0xffff0000, v30
	s_waitcnt lgkmcnt(3)
	v_and_b32_e32 v30, 0xffff0000, v111
	v_cvt_pk_bf16_f32 v25, v54, v55
	s_waitcnt vmcnt(7)
	v_mov_b32_e32 v54, v47
	v_mov_b32_e32 v60, v35
	v_lshlrev_b32_e32 v35, 16, v111
	v_mul_f32_e32 v63, v107, v30
	v_mov_b32_e32 v47, v49
	v_mov_b32_e32 v55, v48
	v_mul_f32_e32 v64, v107, v35
	v_pk_mul_f32 v[46:47], v[46:47], v[62:63]
	v_and_b32_e32 v49, 0xffff0000, v31
	v_pk_fma_f32 v[46:47], v[64:65], v[54:55], v[46:47]
	v_mov_b32_e32 v56, v43
	v_cvt_pk_bf16_f32 v30, v46, v47
	v_lshlrev_b32_e32 v46, 16, v31
	s_waitcnt lgkmcnt(2)
	v_and_b32_e32 v31, 0xffff0000, v97
	v_lshlrev_b32_e32 v35, 16, v97
	v_mul_f32_e32 v47, v107, v31
	v_mov_b32_e32 v43, v45
	v_mov_b32_e32 v57, v44
	v_mul_f32_e32 v48, v107, v35
	v_pk_mul_f32 v[42:43], v[42:43], v[46:47]
	v_and_b32_e32 v45, 0xffff0000, v32
	v_pk_fma_f32 v[42:43], v[48:49], v[56:57], v[42:43]
	v_mov_b32_e32 v58, v39
	v_cvt_pk_bf16_f32 v31, v42, v43
	v_lshlrev_b32_e32 v42, 16, v32
	s_waitcnt lgkmcnt(1)
	v_and_b32_e32 v32, 0xffff0000, v81
	v_lshlrev_b32_e32 v35, 16, v81
	v_mul_f32_e32 v43, v107, v32
	v_mov_b32_e32 v39, v41
	v_mov_b32_e32 v59, v40
	v_mul_f32_e32 v44, v107, v35
	v_pk_mul_f32 v[38:39], v[38:39], v[42:43]
	s_waitcnt lgkmcnt(0)
	v_lshlrev_b32_e32 v35, 16, v80
	v_pk_fma_f32 v[38:39], v[44:45], v[58:59], v[38:39]
	v_and_b32_e32 v41, 0xffff0000, v33
	v_cvt_pk_bf16_f32 v32, v38, v39
	v_lshlrev_b32_e32 v38, 16, v33
	v_and_b32_e32 v33, 0xffff0000, v80
	global_load_dwordx4 v[42:45], v[70:71], off
	s_nop 0
	global_load_dwordx4 v[70:73], v[148:149], off offset:128
	global_load_dwordx4 v[78:81], v[150:151], off offset:128
	v_mul_f32_e32 v40, v107, v35
	v_mul_f32_e32 v39, v107, v33
	v_mov_b32_e32 v35, v37
	v_mov_b32_e32 v61, v36
	v_pk_mul_f32 v[34:35], v[34:35], v[38:39]
	s_lshr_b32 s4, s8, 8
	v_pk_fma_f32 v[34:35], v[40:41], v[60:61], v[34:35]
	s_movk_i32 s3, 0xd0
	v_lshlrev_b32_e32 v105, 3, v109
	s_mul_i32 s4, s4, 0x12800
	v_cvt_pk_bf16_f32 v33, v34, v35
	v_mul_lo_u32 v34, v171, s3
	v_lshlrev_b32_e32 v35, 4, v96
	v_add3_u32 v177, s4, v34, v35
	v_mul_lo_u32 v34, v172, s3
	v_lshlrev_b32_e32 v35, 4, v100
	v_lshl_or_b32 v38, v105, 1, s4
	v_mul_u32_u24_e32 v39, 0x68, v108
	v_add3_u32 v178, s4, v34, v35
	v_mul_lo_u32 v34, v173, s3
	v_lshlrev_b32_e32 v35, 1, v102
	s_movk_i32 s3, 0x90
	v_lshl_add_u32 v183, v39, 1, v38
	v_xor_b32_e32 v38, 16, v191
	s_lshl_b32 s34, s6, 1
	v_add3_u32 v179, s4, v34, v35
	v_mul_lo_u32 v34, v101, s3
	v_cmp_lt_i32_e32 vcc, v38, v110
	s_min_u32 s5, s34, 31
	v_add3_u32 v180, s4, v34, v104
	v_mul_lo_u32 v34, v116, s3
	v_cndmask_b32_e32 v38, v191, v38, vcc
	s_add_i32 s5, s5, 3
	v_add3_u32 v181, s4, v34, v104
	v_mov_b32_e32 v34, v94
	v_mov_b32_e32 v35, v12
	v_lshlrev_b32_e32 v170, 2, v38
	v_mul_u32_u24_e32 v38, 0x48, v108
	s_and_b32 s36, s5, 62
	v_mov_b32_e32 v36, v98
	v_mov_b32_e32 v37, v12
	v_mov_b32_e32 v107, v12
	v_lshlrev_b32_e32 v182, 2, v109
	v_lshlrev_b32_e32 v38, 1, v38
	v_lshl_add_u64 v[152:153], v[34:35], 1, s[56:57]
	v_lshl_add_u64 v[34:35], v[146:147], 1, s[60:61]
	v_mov_b32_e32 v176, 0
	s_mov_b32 s35, 3
	s_waitcnt vmcnt(9)
	ds_write_b128 v177, v[50:53]
	s_waitcnt vmcnt(8)
	ds_write_b128 v178, v[74:77]
	s_waitcnt vmcnt(7)
	ds_write_b128 v179, v[82:85]
	s_waitcnt vmcnt(6)
	ds_write_b128 v180, v[90:93] offset:26624
	s_add_i32 s37, s36, -1
	v_add3_u32 v184, s4, v38, v105
	v_lshl_add_u64 v[154:155], v[94:95], 1, v[34:35]
	v_lshl_add_u64 v[156:157], v[36:37], 1, s[56:57]
	v_lshl_add_u64 v[158:159], v[98:99], 1, v[34:35]
	v_lshl_add_u64 v[160:161], v[106:107], 1, s[56:57]
	v_lshl_add_u64 v[162:163], v[102:103], 1, v[34:35]
	v_mov_b32_e32 v202, 0xff800000
	v_mov_b32_e32 v185, v182
	v_mov_b32_e32 v201, 0
	v_mov_b32_e32 v203, 0xff800000
	v_mov_b32_e32 v34, 0
	v_mov_b32_e32 v35, v176
	v_mov_b32_e32 v36, v176
	v_mov_b32_e32 v37, v176
	v_mov_b32_e32 v66, 0
	v_mov_b32_e32 v67, v176
	v_mov_b32_e32 v68, v176
	v_mov_b32_e32 v69, v176
	v_mov_b32_e32 v38, 0
	v_mov_b32_e32 v39, v176
	v_mov_b32_e32 v40, v176
	v_mov_b32_e32 v41, v176
	v_mov_b32_e32 v74, 0
	v_mov_b32_e32 v75, v176
	v_mov_b32_e32 v76, v176
	v_mov_b32_e32 v77, v176
	v_mov_b32_e32 v46, 0
	v_mov_b32_e32 v47, v176
	v_mov_b32_e32 v48, v176
	v_mov_b32_e32 v49, v176
	v_mov_b32_e32 v90, 0
	v_mov_b32_e32 v91, v176
	v_mov_b32_e32 v92, v176
	v_mov_b32_e32 v93, v176
	v_mov_b32_e32 v62, 0
	v_mov_b32_e32 v63, v176
	v_mov_b32_e32 v64, v176
	v_mov_b32_e32 v65, v176
	v_mov_b32_e32 v94, 0
	v_mov_b32_e32 v95, v176
	v_mov_b32_e32 v96, v176
	v_mov_b32_e32 v97, v176
	s_waitcnt vmcnt(5)
	ds_write_b128 v181, v[86:89] offset:26624
	s_waitcnt lgkmcnt(0)
	s_barrier
	.p2align 6

; template <int EPI>
; __device__ __forceinline__ void gemm_wide(const WS& ws, const bf16_t* A, int lda, const bf16_t* __restrict__ W, int K, float invK,
;                                           int ntn, int ntiles, int bid) {
;     ...
;       c_id += G;
;     };
;     issue();
;     store(0);
;     __syncthreads();
; #pragma unroll 1
;     for (int s = 0; s < S; ++s) {
;       issue();
;       compute(s & 1);
;       if (++c_kt == nk) { c_kt = 0; tile_end(); }
;       store((s + 1) & 1);
;       __syncthreads();
;     }
.LBB0_1038:
	s_load_dwordx2 s[8:9], s[0:1], 0x110
	s_add_i32 s4, s65, 1
	s_cmp_eq_u32 s4, 16
	s_cselect_b32 s65, 0, s4
	s_waitcnt lgkmcnt(0)
	s_cselect_b32 s5, s8, 0
	s_add_i32 s66, s5, s66
	s_cmp_lg_u32 s34, s35
	s_barrier
	s_cbranch_scc0 .LBB0_1104
	.p2align 6

; __device__ __forceinline__ int half_id() { return __builtin_amdgcn_readfirstlane((int)(threadIdx.x >> 8)); }
; __device__ __forceinline__ int opaque_tid() { int t = threadIdx.x & 255; asm volatile("" : "+v"(t)); return t; }
; #define smem (smem_all + half_id() * SMEM_BYTES)
; __device__ __forceinline__ void gemm_rem_splitk(const WS& ws, const bf16_t* A, const bf16_t* __restrict__ W, int bid) {
;   unsigned char* As = smem;
;   unsigned char* Bs = smem + 32768;
;   float* xacc = (float*)(smem_all + SMEM_BYTES);
;   float* xss = (float*)(smem_all + SMEM_BYTES + 65536);
;   float* rsl = (float*)(smem_all + 65536);
;   const int tid = opaque_tid(), lane = tid & 63, w = tid >> 6, wm = w >> 1, wn = w & 1, lr = lane & 15, lq = lane >> 4;
;   const int hh = half_id();
;   if (bid < 169) {
;     int rt, nt;
;     if (bid < 129) { rt = bid; nt = 40; } else { rt = 128; nt = bid - 129; }
;     f32x4 acc[4][4];
; #pragma unroll
;     for (int a = 0; a < 4; ++a)
; #pragma unroll
;       for (int b = 0; b < 4; ++b) acc[a][b] = (f32x4){0.f, 0.f, 0.f, 0.f};
;     u32x4 ra[4], rb[4];
;     float ss[4] = {0.f, 0.f, 0.f, 0.f};
;     const int srow = tid >> 3;
;     const int soff = srow * 128 + (((tid & 7) ^ (srow & 7)) << 4);
;     const bf16_t* ap = A + (size_t)(rt * 128 + srow) * 1024 + hh * 512 + (tid & 7) * 8;
;     const bf16_t* wp = W + (size_t)(nt * 128 + srow) * 1024 + hh * 512 + (tid & 7) * 8;
;     auto issue = [&](int kt) {
; #pragma unroll
;       for (int i = 0; i < 4; ++i) {
;         ra[i] = *(const u32x4*)(ap + (size_t)i * 32 * 1024 + kt * 64);
;         rb[i] = *(const u32x4*)(wp + (size_t)i * 32 * 1024 + kt * 64);
;       }
;     };
;     auto store = [&](int buf) {
; #pragma unroll
;       for (int i = 0; i < 4; ++i) {
;         ss[i] += sumsq8(__builtin_bit_cast(bf16x8, ra[i]));
;         *(u32x4*)(As + buf * 16384 + i * 4096 + soff) = ra[i];
;         *(u32x4*)(Bs + buf * 16384 + i * 4096 + soff) = rb[i];
;       }
;     };
;     issue(0);
;     store(0);
;     __syncthreads();
.LBB0_1104:
	s_mov_b32 s5, s68
	s_barrier
	v_readfirstlane_b32 s9, v175
	v_mov_b32_e32 v13, v186
	s_cmpk_gt_i32 s5, 0xa8
	s_cbranch_scc1 .LBB0_1146
	v_readlane_b32 s12, v240, 27
	v_readlane_b32 s13, v240, 28
	s_lshr_b64 s[6:7], s[12:13], 1
	s_lshl_b32 s7, s5, 7
	s_lshr_b32 s11, s9, 8
	s_add_i32 s4, s7, 0xffffbf80
	s_cmpk_lt_i32 s5, 0x81
	s_cselect_b32 s5, s7, 0x4000
	v_ashrrev_i32_e32 v106, 3, v13
	v_add_u32_e32 v0, s5, v106
	v_ashrrev_i32_e32 v1, 31, v0
	v_lshlrev_b64 v[0:1], 11, v[0:1]
	s_cselect_b32 s8, 0x1400, s4
	v_and_b32_e32 v107, 7, v13
	v_lshl_add_u64 v[0:1], s[58:59], 0, v[0:1]
	s_lshl_b32 s92, s11, 10
	v_lshl_add_u64 v[0:1], v[0:1], 0, s[92:93]
	v_lshlrev_b32_e32 v2, 4, v107
	v_mov_b32_e32 v3, v12
	v_lshl_add_u64 v[98:99], v[0:1], 0, v[2:3]
	v_add_u32_e32 v0, s8, v106
	v_ashrrev_i32_e32 v1, 31, v0
	v_lshlrev_b64 v[0:1], 11, v[0:1]
	v_lshl_add_u64 v[4:5], s[48:49], 0, v[0:1]
	s_mov_b32 s7, 0x10000
	v_lshl_add_u64 v[4:5], v[4:5], 0, s[92:93]
	v_add_co_u32_e32 v6, vcc, s7, v98
	v_lshl_add_u64 v[4:5], v[4:5], 0, v[2:3]
	s_nop 0
	v_addc_co_u32_e32 v7, vcc, 0, v99, vcc
	global_load_dwordx4 v[66:69], v[98:99], off
	global_load_dwordx4 v[74:77], v[6:7], off
	v_add_co_u32_e32 v6, vcc, s7, v4
	s_mov_b32 s3, 0x20000
	s_nop 0
	v_addc_co_u32_e32 v7, vcc, 0, v5, vcc
	global_load_dwordx4 v[78:81], v[6:7], off
	v_add_co_u32_e32 v6, vcc, s3, v98
	global_load_dwordx4 v[70:73], v[4:5], off
	s_nop 0
	v_addc_co_u32_e32 v7, vcc, 0, v99, vcc
	global_load_dwordx4 v[82:85], v[6:7], off
	v_add_co_u32_e32 v6, vcc, s3, v4
	s_mov_b32 s3, 0x30000
	s_nop 0
	v_addc_co_u32_e32 v7, vcc, 0, v5, vcc
	global_load_dwordx4 v[86:89], v[6:7], off
	v_add_co_u32_e32 v6, vcc, s3, v98
	s_mul_i32 s11, s11, 0x12800
	s_nop 0
	v_addc_co_u32_e32 v7, vcc, 0, v99, vcc
	global_load_dwordx4 v[90:93], v[6:7], off
	v_add_co_u32_e32 v4, vcc, s3, v4
	s_movk_i32 s3, 0x70
	s_nop 0
	v_addc_co_u32_e32 v5, vcc, 0, v5, vcc
	global_load_dwordx4 v[94:97], v[4:5], off
	v_xor_b32_e32 v5, v106, v13
	v_lshlrev_b32_e32 v4, 7, v106
	v_lshlrev_b32_e32 v5, 4, v5
	v_and_or_b32 v4, v5, s3, v4
	v_add_u32_e32 v108, s11, v4
	v_mad_u64_u32 v[0:1], s[6:7], s6, v195, v[0:1]
	s_lshr_b32 s6, s13, 1
	s_mul_i32 s6, s6, 0x1680000
	v_bfe_u32 v130, v13, 6, 1
	v_and_b32_e32 v131, 15, v13
	v_lshrrev_b32_e32 v3, 4, v13
	v_add_u32_e32 v1, s6, v1
	s_add_u32 s6, s30, s92
	v_ashrrev_i32_e32 v139, 7, v13
	v_bfe_u32 v138, v13, 4, 2
	v_bitop3_b32 v3, v3, v107, 3 bitop3:0x6c
	v_or_b32_e32 v0, v0, v2
	s_addc_u32 s7, s31, 0
	v_lshlrev_b32_e32 v111, 4, v3
	v_bitop3_b32 v3, v138, v107, 4 bitop3:0x36
	v_lshl_add_u64 v[104:105], s[6:7], 0, v[0:1]
	v_mov_b32_e32 v0, 0
	s_mov_b32 s82, 0x10000
	s_mov_b32 s2, 0x20000
	s_mov_b32 s10, 0
	v_lshlrev_b32_e32 v112, 4, v3
	s_mov_b64 s[6:7], 0
	v_mov_b32_e32 v1, v0
	v_mov_b32_e32 v2, v0
	v_mov_b32_e32 v3, v0
	v_mov_b32_e32 v42, v0
	v_mov_b32_e32 v43, v0
	v_mov_b32_e32 v44, v0
	v_mov_b32_e32 v45, v0
	v_mov_b32_e32 v46, v0
	v_mov_b32_e32 v47, v0
	v_mov_b32_e32 v48, v0
	v_mov_b32_e32 v49, v0
	v_mov_b32_e32 v50, v0
	v_mov_b32_e32 v51, v0
	v_mov_b32_e32 v52, v0
	v_mov_b32_e32 v53, v0
	v_mov_b32_e32 v54, v0
	v_mov_b32_e32 v55, v0
	v_mov_b32_e32 v56, v0
	v_mov_b32_e32 v57, v0
	v_mov_b32_e32 v58, v0
	s_waitcnt vmcnt(7)
	v_and_b32_e32 v6, 0xffff0000, v66
	s_waitcnt vmcnt(6)
	v_and_b32_e32 v7, 0xffff0000, v74
	v_lshlrev_b32_e32 v4, 16, v66
	v_lshlrev_b32_e32 v5, 16, v74
	v_pk_mul_f32 v[6:7], v[6:7], v[6:7]
	v_lshlrev_b32_e32 v8, 16, v67
	v_lshlrev_b32_e32 v9, 16, v75
	v_pk_fma_f32 v[4:5], v[4:5], v[4:5], v[6:7]
	v_and_b32_e32 v10, 0xffff0000, v67
	v_and_b32_e32 v11, 0xffff0000, v75
	v_pk_fma_f32 v[4:5], v[8:9], v[8:9], v[4:5]
	v_lshlrev_b32_e32 v14, 16, v68
	v_lshlrev_b32_e32 v15, 16, v76
	v_pk_fma_f32 v[4:5], v[10:11], v[10:11], v[4:5]
	v_and_b32_e32 v16, 0xffff0000, v68
	v_and_b32_e32 v17, 0xffff0000, v76
	v_pk_fma_f32 v[4:5], v[14:15], v[14:15], v[4:5]
	v_lshlrev_b32_e32 v18, 16, v69
	v_lshlrev_b32_e32 v19, 16, v77
	v_pk_fma_f32 v[4:5], v[16:17], v[16:17], v[4:5]
	v_and_b32_e32 v20, 0xffff0000, v69
	v_and_b32_e32 v21, 0xffff0000, v77
	s_waitcnt vmcnt(3)
	v_and_b32_e32 v24, 0xffff0000, v82
	v_pk_fma_f32 v[4:5], v[18:19], v[18:19], v[4:5]
	v_lshlrev_b32_e32 v22, 16, v82
	s_waitcnt vmcnt(1)
	v_and_b32_e32 v25, 0xffff0000, v90
	v_pk_fma_f32 v[100:101], v[20:21], v[20:21], v[4:5]
	v_lshlrev_b32_e32 v23, 16, v90
	v_pk_mul_f32 v[4:5], v[24:25], v[24:25]
	v_lshlrev_b32_e32 v7, 16, v91
	v_pk_fma_f32 v[4:5], v[22:23], v[22:23], v[4:5]
	v_lshlrev_b32_e32 v6, 16, v83
	v_pk_fma_f32 v[4:5], v[6:7], v[6:7], v[4:5]
	v_and_b32_e32 v7, 0xffff0000, v91
	v_and_b32_e32 v6, 0xffff0000, v83
	v_pk_fma_f32 v[4:5], v[6:7], v[6:7], v[4:5]
	v_lshlrev_b32_e32 v7, 16, v92
	v_lshlrev_b32_e32 v6, 16, v84
	v_pk_fma_f32 v[4:5], v[6:7], v[6:7], v[4:5]
	v_and_b32_e32 v7, 0xffff0000, v92
	v_and_b32_e32 v6, 0xffff0000, v84
	v_pk_fma_f32 v[4:5], v[6:7], v[6:7], v[4:5]
	v_lshlrev_b32_e32 v7, 16, v93
	v_lshlrev_b32_e32 v6, 16, v85
	v_pk_fma_f32 v[4:5], v[6:7], v[6:7], v[4:5]
	v_and_b32_e32 v7, 0xffff0000, v93
	v_and_b32_e32 v6, 0xffff0000, v85
	v_pk_fma_f32 v[102:103], v[6:7], v[6:7], v[4:5]
	v_lshlrev_b32_e32 v4, 7, v131
	v_lshl_add_u32 v5, v130, 13, s11
	v_or_b32_e32 v109, v5, v4
	v_lshl_add_u32 v5, v139, 13, s11
	v_or_b32_e32 v110, v5, v4
	v_mov_b32_e32 v4, v0
	v_mov_b32_e32 v5, v0
	v_mov_b32_e32 v6, v0
	v_mov_b32_e32 v7, v0
	v_mov_b32_e32 v8, v0
	v_mov_b32_e32 v9, v0
	v_mov_b32_e32 v10, v0
	v_mov_b32_e32 v11, v0
	v_mov_b32_e32 v14, v0
	v_mov_b32_e32 v15, v0
	v_mov_b32_e32 v16, v0
	v_mov_b32_e32 v17, v0
	v_mov_b32_e32 v18, v0
	v_mov_b32_e32 v19, v0
	v_mov_b32_e32 v20, v0
	v_mov_b32_e32 v21, v0
	v_mov_b32_e32 v22, v0
	v_mov_b32_e32 v23, v0
	v_mov_b32_e32 v24, v0
	v_mov_b32_e32 v25, v0
	v_mov_b32_e32 v59, v0
	v_mov_b32_e32 v60, v0
	v_mov_b32_e32 v61, v0
	v_mov_b32_e32 v62, v0
	v_mov_b32_e32 v63, v0
	v_mov_b32_e32 v64, v0
	v_mov_b32_e32 v65, v0
	v_mov_b32_e32 v26, v0
	v_mov_b32_e32 v27, v0
	v_mov_b32_e32 v28, v0
	v_mov_b32_e32 v29, v0
	v_mov_b32_e32 v30, v0
	v_mov_b32_e32 v31, v0
	v_mov_b32_e32 v32, v0
	v_mov_b32_e32 v33, v0
	v_mov_b32_e32 v34, v0
	v_mov_b32_e32 v35, v0
	v_mov_b32_e32 v36, v0
	v_mov_b32_e32 v37, v0
	v_mov_b32_e32 v38, v0
	v_mov_b32_e32 v39, v0
	v_mov_b32_e32 v40, v0
	v_mov_b32_e32 v41, v0
	ds_write_b128 v108, v[66:69]
	ds_write_b128 v108, v[70:73] offset:32768
	ds_write_b128 v108, v[74:77] offset:4096
	ds_write_b128 v108, v[78:81] offset:36864
	ds_write_b128 v108, v[82:85] offset:8192
	ds_write_b128 v108, v[86:89] offset:40960
	ds_write_b128 v108, v[90:93] offset:12288
	s_waitcnt vmcnt(0)
	ds_write_b128 v108, v[94:97] offset:45056
	s_waitcnt lgkmcnt(0)
	s_barrier
	s_branch .LBB0_1107
	.p2align 6

; __device__ __forceinline__ void rglru_unit(const Params& p, const WS& ws, int j, int u, bool dry = false) {
;     ...
;   float ba[2][4], bx[2][4], sp[2][4];
; #pragma unroll
;   for (int mt = 0; mt < 2; ++mt)
; #pragma unroll
;     for (int jj = 0; jj < 4; ++jj) {
;       const int ch = j * 1024 + 128 * g + 32 * jq + 16 * mt + 4 * lq + jj;
;       ba[mt][jj] = p.ab_gate_a_b[ch]; bx[mt][jj] = p.ab_gate_x_b[ch];
;       sp[mt][jj] = 8.f * log1pf(__expf(-p.ab_lam[ch]));
;     }
.LBB0_1375:
	s_or_b64 exec, exec, s[6:7]
	s_waitcnt vmcnt(1)
	v_mul_f32_e32 v13, 0xbfb8aa3b, v56
	v_exp_f32_e32 v13, v13
	s_mov_b32 s3, 0x3f2aaaab
	s_mov_b32 s10, 0x3f317218
	s_mov_b32 s11, 0x33800000
	v_add_f32_e32 v15, 1.0, v13
	v_add_f32_e32 v56, -1.0, v15
	v_sub_f32_e32 v67, v56, v15
	v_frexp_mant_f32_e32 v63, v15
	v_cvt_f64_f32_e32 v[70:71], v15
	v_sub_f32_e32 v56, v13, v56
	v_add_f32_e32 v67, 1.0, v67
	v_add_f32_e32 v56, v56, v67
	v_frexp_exp_i32_f64_e32 v67, v[70:71]
	v_cmp_gt_f32_e32 vcc, s3, v63
	s_lshl_b32 s92, s9, 1
	s_movk_i32 s9, 0x84
	v_subbrev_co_u32_e32 v63, vcc, 0, v67, vcc
	v_sub_u32_e32 v67, 0, v63
	v_ldexp_f32 v15, v15, v67
	v_ldexp_f32 v56, v56, v67
	v_add_f32_e32 v67, -1.0, v15
	v_add_f32_e32 v71, 1.0, v15
	v_add_f32_e32 v69, 1.0, v67
	v_add_f32_e32 v72, -1.0, v71
	v_sub_f32_e32 v69, v15, v69
	v_sub_f32_e32 v15, v15, v72
	v_add_f32_e32 v15, v56, v15
	v_add_f32_e32 v69, v56, v69
	v_add_f32_e32 v56, v71, v15
	v_rcp_f32_e32 v72, v56
	v_add_f32_e32 v70, v67, v69
	v_sub_f32_e32 v67, v70, v67
	v_sub_f32_e32 v67, v69, v67
	v_sub_f32_e32 v69, v56, v71
	v_sub_f32_e32 v15, v15, v69
	v_mul_f32_e32 v69, v70, v72
	v_mul_f32_e32 v71, v56, v69
	v_fma_f32 v73, v69, v56, -v71
	v_fmac_f32_e32 v73, v69, v15
	v_add_f32_e32 v74, v71, v73
	v_sub_f32_e32 v75, v70, v74
	v_sub_f32_e32 v70, v70, v75
	v_sub_f32_e32 v71, v74, v71
	v_sub_f32_e32 v70, v70, v74
	v_add_f32_e32 v67, v67, v70
	v_sub_f32_e32 v70, v71, v73
	v_add_f32_e32 v67, v70, v67
	v_add_f32_e32 v70, v75, v67
	v_mul_f32_e32 v71, v72, v70
	v_mul_f32_e32 v73, v56, v71
	v_fma_f32 v56, v71, v56, -v73
	v_fmac_f32_e32 v56, v71, v15
	v_sub_f32_e32 v15, v75, v70
	v_add_f32_e32 v15, v67, v15
	v_add_f32_e32 v67, v73, v56
	v_sub_f32_e32 v74, v70, v67
	v_sub_f32_e32 v70, v70, v74
	v_sub_f32_e32 v73, v67, v73
	v_sub_f32_e32 v67, v70, v67
	v_add_f32_e32 v15, v15, v67
	v_sub_f32_e32 v56, v73, v56
	v_cvt_f32_i32_e32 v63, v63
	v_add_f32_e32 v15, v56, v15
	v_add_f32_e32 v56, v69, v71
	v_add_f32_e32 v15, v74, v15
	v_sub_f32_e32 v67, v56, v69
	v_mul_f32_e32 v15, v72, v15
	v_sub_f32_e32 v67, v71, v67
	v_add_f32_e32 v15, v67, v15
	v_mul_f32_e32 v71, 0x3f317218, v63
	v_add_f32_e32 v67, v56, v15
	v_fma_f32 v72, v63, s10, -v71
	v_mul_f32_e32 v69, v67, v67
	v_fmac_f32_e32 v72, 0xb102e308, v63
	v_sub_f32_e32 v56, v67, v56
	v_fmamk_f32 v70, v69, 0x3e9b6dac, v192
	v_sub_f32_e32 v15, v15, v56
	v_add_f32_e32 v56, v71, v72
	v_fmaak_f32 v70, v69, v70, 0x3f2aaada
	v_sub_f32_e32 v63, v56, v71
	v_ldexp_f32 v71, v67, 1
	v_mul_f32_e32 v67, v67, v69
	v_mul_f32_e32 v67, v67, v70
	v_add_f32_e32 v69, v71, v67
	v_sub_f32_e32 v70, v69, v71
	v_ldexp_f32 v15, v15, 1
	v_sub_f32_e32 v67, v67, v70
	v_add_f32_e32 v15, v15, v67
	v_add_f32_e32 v67, v69, v15
	v_sub_f32_e32 v69, v67, v69
	v_sub_f32_e32 v15, v15, v69
	v_add_f32_e32 v69, v56, v67
	v_sub_f32_e32 v70, v69, v56
	v_sub_f32_e32 v71, v69, v70
	v_sub_f32_e32 v63, v72, v63
	v_sub_f32_e32 v56, v56, v71
	v_sub_f32_e32 v67, v67, v70
	v_add_f32_e32 v56, v67, v56
	v_add_f32_e32 v67, v63, v15
	v_sub_f32_e32 v70, v67, v63
	v_sub_f32_e32 v71, v67, v70
	v_sub_f32_e32 v63, v63, v71
	v_sub_f32_e32 v15, v15, v70
	v_add_f32_e32 v56, v67, v56
	v_add_f32_e32 v15, v15, v63
	v_add_f32_e32 v63, v69, v56
	v_sub_f32_e32 v67, v63, v69
	v_sub_f32_e32 v56, v56, v67
	v_add_f32_e32 v15, v15, v56
	v_add_f32_e32 v15, v63, v15
	v_cmp_neq_f32_e32 vcc, s21, v13
	v_mul_f32_e32 v56, 0xbfb8aa3b, v57
	v_exp_f32_e32 v63, v56
	v_cndmask_b32_e32 v15, v199, v15, vcc
	v_cmp_ngt_f32_e32 vcc, -1.0, v13
	s_mov_b32 s6, 0
	s_mov_b32 s7, 1
	v_cndmask_b32_e32 v15, v200, v15, vcc
	v_cmp_neq_f32_e32 vcc, -1.0, v13
	v_lshl_add_u32 v115, v60, 2, s8
	v_cmp_lt_i32_e64 s[38:39], 1, v66
	v_cndmask_b32_e32 v15, v194, v15, vcc
	v_cmp_lt_f32_e64 vcc, |v13|, s11
	v_cmp_lt_i32_e64 s[40:41], 2, v66
	v_cmp_lt_i32_e64 s[42:43], 3, v66
	v_cndmask_b32_e32 v13, v15, v13, vcc
	v_mul_f32_e32 v89, 0x41000000, v13
	v_add_f32_e32 v13, 1.0, v63
	v_add_f32_e32 v15, -1.0, v13
	v_sub_f32_e32 v56, v15, v13
	v_add_f32_e32 v56, 1.0, v56
	v_sub_f32_e32 v15, v63, v15
	v_add_f32_e32 v15, v15, v56
	v_frexp_mant_f32_e32 v67, v13
	v_cvt_f64_f32_e32 v[56:57], v13
	v_frexp_exp_i32_f64_e32 v56, v[56:57]
	v_cmp_gt_f32_e32 vcc, s3, v67
	v_cmp_lt_i32_e64 s[44:45], 4, v66
	v_cmp_lt_i32_e64 s[46:47], 5, v66
	v_subbrev_co_u32_e32 v56, vcc, 0, v56, vcc
	v_sub_u32_e32 v57, 0, v56
	v_ldexp_f32 v13, v13, v57
	v_ldexp_f32 v15, v15, v57
	v_add_f32_e32 v57, -1.0, v13
	v_add_f32_e32 v70, 1.0, v13
	v_add_f32_e32 v67, 1.0, v57
	v_add_f32_e32 v71, -1.0, v70
	v_sub_f32_e32 v67, v13, v67
	v_sub_f32_e32 v13, v13, v71
	v_add_f32_e32 v13, v15, v13
	v_add_f32_e32 v67, v15, v67
	v_add_f32_e32 v15, v70, v13
	v_rcp_f32_e32 v71, v15
	v_add_f32_e32 v69, v57, v67
	v_sub_f32_e32 v57, v69, v57
	v_sub_f32_e32 v57, v67, v57
	v_sub_f32_e32 v67, v15, v70
	v_sub_f32_e32 v13, v13, v67
	v_mul_f32_e32 v67, v69, v71
	v_mul_f32_e32 v70, v15, v67
	v_fma_f32 v72, v67, v15, -v70
	v_fmac_f32_e32 v72, v67, v13
	v_add_f32_e32 v73, v70, v72
	v_sub_f32_e32 v74, v69, v73
	v_sub_f32_e32 v69, v69, v74
	v_sub_f32_e32 v70, v73, v70
	v_sub_f32_e32 v69, v69, v73
	v_add_f32_e32 v57, v57, v69
	v_sub_f32_e32 v69, v70, v72
	v_add_f32_e32 v57, v69, v57
	v_add_f32_e32 v69, v74, v57
	v_mul_f32_e32 v70, v71, v69
	v_mul_f32_e32 v72, v15, v70
	v_fma_f32 v15, v70, v15, -v72
	v_fmac_f32_e32 v15, v70, v13
	v_sub_f32_e32 v13, v74, v69
	v_add_f32_e32 v13, v57, v13
	v_add_f32_e32 v57, v72, v15
	v_sub_f32_e32 v73, v69, v57
	v_sub_f32_e32 v69, v69, v73
	v_sub_f32_e32 v72, v57, v72
	v_sub_f32_e32 v57, v69, v57
	v_add_f32_e32 v13, v13, v57
	v_sub_f32_e32 v15, v72, v15
	v_cvt_f32_i32_e32 v56, v56
	v_add_f32_e32 v13, v15, v13
; __device__ __forceinline__ void rglru_unit(const Params& p, const WS& ws, int j, int u, bool dry = false) {
;     ...
;   float ba[2][4], bx[2][4], sp[2][4];
; #pragma unroll
;   for (int mt = 0; mt < 2; ++mt)
; #pragma unroll
;     for (int jj = 0; jj < 4; ++jj) {
;       const int ch = j * 1024 + 128 * g + 32 * jq + 16 * mt + 4 * lq + jj;
;       ba[mt][jj] = p.ab_gate_a_b[ch]; bx[mt][jj] = p.ab_gate_x_b[ch];
;       sp[mt][jj] = 8.f * log1pf(__expf(-p.ab_lam[ch]));
;     }
;     ...
;   __syncthreads();
	v_add_f32_e32 v15, v67, v70
	v_add_f32_e32 v13, v73, v13
	v_sub_f32_e32 v57, v15, v67
	v_mul_f32_e32 v13, v71, v13
	v_sub_f32_e32 v57, v70, v57
	v_add_f32_e32 v13, v57, v13
	v_mul_f32_e32 v70, 0x3f317218, v56
	v_add_f32_e32 v57, v15, v13
	v_fma_f32 v71, v56, s10, -v70
	v_mul_f32_e32 v67, v57, v57
	v_fmac_f32_e32 v71, 0xb102e308, v56
	v_sub_f32_e32 v15, v57, v15
	v_fmamk_f32 v69, v67, 0x3e9b6dac, v192
	v_sub_f32_e32 v13, v13, v15
	v_add_f32_e32 v15, v70, v71
	v_fmaak_f32 v69, v67, v69, 0x3f2aaada
	v_sub_f32_e32 v56, v15, v70
	v_ldexp_f32 v70, v57, 1
	v_mul_f32_e32 v57, v57, v67
	v_mul_f32_e32 v57, v57, v69
	v_add_f32_e32 v67, v70, v57
	v_sub_f32_e32 v69, v67, v70
	v_ldexp_f32 v13, v13, 1
	v_sub_f32_e32 v57, v57, v69
	v_add_f32_e32 v13, v13, v57
	v_add_f32_e32 v57, v67, v13
	v_sub_f32_e32 v67, v57, v67
	v_sub_f32_e32 v13, v13, v67
	v_add_f32_e32 v67, v15, v57
	v_sub_f32_e32 v69, v67, v15
	v_sub_f32_e32 v70, v67, v69
	v_sub_f32_e32 v56, v71, v56
	v_sub_f32_e32 v15, v15, v70
	v_sub_f32_e32 v57, v57, v69
	v_add_f32_e32 v15, v57, v15
	v_add_f32_e32 v57, v56, v13
	v_sub_f32_e32 v69, v57, v56
	v_sub_f32_e32 v70, v57, v69
	v_sub_f32_e32 v56, v56, v70
	v_sub_f32_e32 v13, v13, v69
	v_add_f32_e32 v15, v57, v15
	v_add_f32_e32 v13, v13, v56
	v_add_f32_e32 v56, v67, v15
	v_sub_f32_e32 v57, v56, v67
	v_sub_f32_e32 v15, v15, v57
	v_add_f32_e32 v13, v13, v15
	v_add_f32_e32 v13, v56, v13
	v_cmp_neq_f32_e32 vcc, s21, v63
	v_mul_f32_e32 v15, 0xbfb8aa3b, v58
	v_exp_f32_e32 v15, v15
	v_cndmask_b32_e32 v13, v199, v13, vcc
	v_cmp_ngt_f32_e32 vcc, -1.0, v63
	v_cmp_lt_i32_e64 s[48:49], 6, v66
	v_cmp_eq_u32_e64 s[50:51], 7, v66
	v_cndmask_b32_e32 v13, v200, v13, vcc
	v_cmp_neq_f32_e32 vcc, -1.0, v63
	v_or_b32_e32 v108, 1, v84
	v_or_b32_e32 v104, 2, v84
	v_cndmask_b32_e32 v13, v194, v13, vcc
	v_cmp_lt_f32_e64 vcc, |v63|, s11
	v_or_b32_e32 v103, 3, v84
	v_or_b32_e32 v102, 4, v84
	v_cndmask_b32_e32 v13, v13, v63, vcc
	v_mul_f32_e32 v93, 0x41000000, v13
	v_add_f32_e32 v13, 1.0, v15
	v_add_f32_e32 v56, -1.0, v13
	v_sub_f32_e32 v57, v56, v13
	v_add_f32_e32 v57, 1.0, v57
	v_sub_f32_e32 v56, v15, v56
	v_add_f32_e32 v58, v56, v57
	v_frexp_mant_f32_e32 v63, v13
	v_cvt_f64_f32_e32 v[56:57], v13
	v_frexp_exp_i32_f64_e32 v56, v[56:57]
	v_cmp_gt_f32_e32 vcc, s3, v63
	v_or_b32_e32 v101, 5, v84
	v_or_b32_e32 v100, 6, v84
	v_subbrev_co_u32_e32 v56, vcc, 0, v56, vcc
	v_sub_u32_e32 v57, 0, v56
	v_ldexp_f32 v13, v13, v57
	v_ldexp_f32 v57, v58, v57
	v_add_f32_e32 v58, -1.0, v13
	v_add_f32_e32 v69, 1.0, v13
	v_add_f32_e32 v63, 1.0, v58
	v_add_f32_e32 v70, -1.0, v69
	v_sub_f32_e32 v63, v13, v63
	v_sub_f32_e32 v13, v13, v70
	v_add_f32_e32 v13, v57, v13
	v_add_f32_e32 v63, v57, v63
	v_add_f32_e32 v57, v69, v13
	v_rcp_f32_e32 v70, v57
	v_add_f32_e32 v67, v58, v63
	v_sub_f32_e32 v58, v67, v58
	v_sub_f32_e32 v58, v63, v58
	v_sub_f32_e32 v63, v57, v69
	v_sub_f32_e32 v13, v13, v63
	v_mul_f32_e32 v63, v67, v70
	v_mul_f32_e32 v69, v57, v63
	v_fma_f32 v71, v63, v57, -v69
	v_fmac_f32_e32 v71, v63, v13
	v_add_f32_e32 v72, v69, v71
	v_sub_f32_e32 v73, v67, v72
	v_sub_f32_e32 v67, v67, v73
	v_sub_f32_e32 v69, v72, v69
	v_sub_f32_e32 v67, v67, v72
	v_add_f32_e32 v58, v58, v67
	v_sub_f32_e32 v67, v69, v71
	v_add_f32_e32 v58, v67, v58
	v_add_f32_e32 v67, v73, v58
	v_mul_f32_e32 v69, v70, v67
	v_mul_f32_e32 v71, v57, v69
	v_fma_f32 v57, v69, v57, -v71
	v_fmac_f32_e32 v57, v69, v13
	v_sub_f32_e32 v13, v73, v67
	v_add_f32_e32 v13, v58, v13
	v_add_f32_e32 v58, v71, v57
	v_sub_f32_e32 v72, v67, v58
	v_sub_f32_e32 v67, v67, v72
	v_sub_f32_e32 v71, v58, v71
	v_sub_f32_e32 v58, v67, v58
	v_add_f32_e32 v13, v13, v58
	v_sub_f32_e32 v57, v71, v57
	v_cvt_f32_i32_e32 v56, v56
	v_add_f32_e32 v13, v57, v13
	v_add_f32_e32 v57, v63, v69
	v_add_f32_e32 v13, v72, v13
	v_sub_f32_e32 v58, v57, v63
	v_mul_f32_e32 v13, v70, v13
	v_sub_f32_e32 v58, v69, v58
	v_add_f32_e32 v13, v58, v13
	v_mul_f32_e32 v69, 0x3f317218, v56
	v_add_f32_e32 v58, v57, v13
	v_fma_f32 v70, v56, s10, -v69
	v_mul_f32_e32 v63, v58, v58
	v_fmac_f32_e32 v70, 0xb102e308, v56
	v_sub_f32_e32 v56, v58, v57
	v_fmamk_f32 v67, v63, 0x3e9b6dac, v192
	v_sub_f32_e32 v13, v13, v56
	v_add_f32_e32 v56, v69, v70
	v_fmaak_f32 v67, v63, v67, 0x3f2aaada
	v_sub_f32_e32 v57, v56, v69
	v_ldexp_f32 v69, v58, 1
	v_mul_f32_e32 v58, v58, v63
	v_mul_f32_e32 v58, v58, v67
	v_add_f32_e32 v63, v69, v58
	v_sub_f32_e32 v67, v63, v69
	v_ldexp_f32 v13, v13, 1
	v_sub_f32_e32 v58, v58, v67
	v_add_f32_e32 v13, v13, v58
	v_add_f32_e32 v58, v63, v13
	v_sub_f32_e32 v63, v58, v63
	v_sub_f32_e32 v13, v13, v63
	v_add_f32_e32 v63, v56, v58
	v_sub_f32_e32 v67, v63, v56
	v_sub_f32_e32 v69, v63, v67
	v_sub_f32_e32 v57, v70, v57
	v_sub_f32_e32 v56, v56, v69
	v_sub_f32_e32 v58, v58, v67
	v_add_f32_e32 v56, v58, v56
	v_add_f32_e32 v58, v57, v13
	v_sub_f32_e32 v67, v58, v57
	v_sub_f32_e32 v69, v58, v67
	v_sub_f32_e32 v57, v57, v69
	v_sub_f32_e32 v13, v13, v67
	v_add_f32_e32 v56, v58, v56
	v_add_f32_e32 v13, v13, v57
	v_add_f32_e32 v57, v63, v56
	v_sub_f32_e32 v58, v57, v63
	v_sub_f32_e32 v56, v56, v58
	v_add_f32_e32 v13, v13, v56
	v_add_f32_e32 v13, v57, v13
	v_cmp_neq_f32_e32 vcc, s21, v15
	v_mul_f32_e32 v56, 0xbfb8aa3b, v59
	v_exp_f32_e32 v58, v56
	v_cndmask_b32_e32 v13, v199, v13, vcc
	v_cmp_ngt_f32_e32 vcc, -1.0, v15
	v_add_u32_e32 v116, v81, v84
	v_add_u32_e32 v117, v80, v84
	v_cndmask_b32_e32 v13, v200, v13, vcc
	v_cmp_neq_f32_e32 vcc, -1.0, v15
	v_add_u32_e32 v118, v79, v84
	s_mov_b32 s12, 0
	v_cndmask_b32_e32 v13, v194, v13, vcc
	v_cmp_lt_f32_e64 vcc, |v15|, s11
	s_barrier
; __device__ __forceinline__ void rglru_unit(const Params& p, const WS& ws, int j, int u, bool dry = false) {
;     ...
;   float ba[2][4], bx[2][4], sp[2][4];
; #pragma unroll
;   for (int mt = 0; mt < 2; ++mt)
; #pragma unroll
;     for (int jj = 0; jj < 4; ++jj) {
;       const int ch = j * 1024 + 128 * g + 32 * jq + 16 * mt + 4 * lq + jj;
;       ba[mt][jj] = p.ab_gate_a_b[ch]; bx[mt][jj] = p.ab_gate_x_b[ch];
;       sp[mt][jj] = 8.f * log1pf(__expf(-p.ab_lam[ch]));
;     }
	s_nop 0
	v_cndmask_b32_e32 v13, v13, v15, vcc
	v_mul_f32_e32 v95, 0x41000000, v13
	v_add_f32_e32 v13, 1.0, v58
	v_add_f32_e32 v15, -1.0, v13
	v_sub_f32_e32 v56, v15, v13
	v_add_f32_e32 v56, 1.0, v56
	v_sub_f32_e32 v15, v58, v15
	v_add_f32_e32 v15, v15, v56
	v_frexp_mant_f32_e32 v59, v13
	v_cvt_f64_f32_e32 v[56:57], v13
	v_frexp_exp_i32_f64_e32 v56, v[56:57]
	v_cmp_gt_f32_e32 vcc, s3, v59
	s_nop 1
	v_subbrev_co_u32_e32 v56, vcc, 0, v56, vcc
	v_sub_u32_e32 v57, 0, v56
	v_ldexp_f32 v13, v13, v57
	v_ldexp_f32 v15, v15, v57
	v_add_f32_e32 v57, -1.0, v13
	v_add_f32_e32 v67, 1.0, v13
	v_add_f32_e32 v59, 1.0, v57
	v_add_f32_e32 v69, -1.0, v67
	v_sub_f32_e32 v59, v13, v59
	v_sub_f32_e32 v13, v13, v69
	v_add_f32_e32 v13, v15, v13
	v_add_f32_e32 v59, v15, v59
	v_add_f32_e32 v15, v67, v13
	v_rcp_f32_e32 v69, v15
	v_add_f32_e32 v63, v57, v59
	v_sub_f32_e32 v57, v63, v57
	v_sub_f32_e32 v57, v59, v57
	v_sub_f32_e32 v59, v15, v67
	v_sub_f32_e32 v13, v13, v59
	v_mul_f32_e32 v59, v63, v69
	v_mul_f32_e32 v67, v15, v59
	v_fma_f32 v70, v59, v15, -v67
	v_fmac_f32_e32 v70, v59, v13
	v_add_f32_e32 v71, v67, v70
	v_sub_f32_e32 v72, v63, v71
	v_sub_f32_e32 v63, v63, v72
	v_sub_f32_e32 v67, v71, v67
	v_sub_f32_e32 v63, v63, v71
	v_add_f32_e32 v57, v57, v63
	v_sub_f32_e32 v63, v67, v70
	v_add_f32_e32 v57, v63, v57
	v_add_f32_e32 v63, v72, v57
	v_mul_f32_e32 v67, v69, v63
	v_mul_f32_e32 v70, v15, v67
	v_fma_f32 v15, v67, v15, -v70
	v_fmac_f32_e32 v15, v67, v13
	v_sub_f32_e32 v13, v72, v63
	v_add_f32_e32 v13, v57, v13
	v_add_f32_e32 v57, v70, v15
	v_sub_f32_e32 v71, v63, v57
	v_sub_f32_e32 v63, v63, v71
	v_sub_f32_e32 v70, v57, v70
	v_sub_f32_e32 v57, v63, v57
	v_add_f32_e32 v13, v13, v57
	v_sub_f32_e32 v15, v70, v15
	v_cvt_f32_i32_e32 v56, v56
	v_add_f32_e32 v13, v15, v13
	v_add_f32_e32 v15, v59, v67
	v_add_f32_e32 v13, v71, v13
	v_sub_f32_e32 v57, v15, v59
	v_mul_f32_e32 v13, v69, v13
	v_sub_f32_e32 v57, v67, v57
	v_add_f32_e32 v13, v57, v13
	v_mul_f32_e32 v67, 0x3f317218, v56
	v_add_f32_e32 v57, v15, v13
	v_fma_f32 v69, v56, s10, -v67
	v_mul_f32_e32 v59, v57, v57
	v_fmac_f32_e32 v69, 0xb102e308, v56
	v_sub_f32_e32 v15, v57, v15
	v_fmamk_f32 v63, v59, 0x3e9b6dac, v192
	v_sub_f32_e32 v13, v13, v15
	v_add_f32_e32 v15, v67, v69
	v_fmaak_f32 v63, v59, v63, 0x3f2aaada
	v_sub_f32_e32 v56, v15, v67
	v_ldexp_f32 v67, v57, 1
	v_mul_f32_e32 v57, v57, v59
	v_mul_f32_e32 v57, v57, v63
	v_add_f32_e32 v59, v67, v57
	v_sub_f32_e32 v63, v59, v67
	v_ldexp_f32 v13, v13, 1
	v_sub_f32_e32 v57, v57, v63
	v_add_f32_e32 v13, v13, v57
	v_add_f32_e32 v57, v59, v13
	v_sub_f32_e32 v59, v57, v59
	v_sub_f32_e32 v13, v13, v59
	v_add_f32_e32 v59, v15, v57
	v_sub_f32_e32 v63, v59, v15
	v_sub_f32_e32 v67, v59, v63
	v_sub_f32_e32 v56, v69, v56
	v_sub_f32_e32 v15, v15, v67
	v_sub_f32_e32 v57, v57, v63
	v_add_f32_e32 v15, v57, v15
	v_add_f32_e32 v57, v56, v13
	v_sub_f32_e32 v63, v57, v56
	v_sub_f32_e32 v67, v57, v63
	v_sub_f32_e32 v56, v56, v67
	v_sub_f32_e32 v13, v13, v63
	v_add_f32_e32 v15, v57, v15
	v_add_f32_e32 v13, v13, v56
	v_add_f32_e32 v56, v59, v15
	v_sub_f32_e32 v57, v56, v59
	v_sub_f32_e32 v15, v15, v57
	v_add_f32_e32 v13, v13, v15
	v_add_f32_e32 v13, v56, v13
	v_cmp_neq_f32_e32 vcc, s21, v58
	s_waitcnt vmcnt(0)
	v_mul_f32_e32 v15, 0xbfb8aa3b, v52
	v_exp_f32_e32 v15, v15
	v_cndmask_b32_e32 v13, v199, v13, vcc
	v_cmp_ngt_f32_e32 vcc, -1.0, v58
	s_nop 1
	v_cndmask_b32_e32 v13, v200, v13, vcc
	v_cmp_neq_f32_e32 vcc, -1.0, v58
	s_nop 1
	v_cndmask_b32_e32 v13, v194, v13, vcc
	v_cmp_lt_f32_e64 vcc, |v58|, s11
	s_nop 1
	v_cndmask_b32_e32 v13, v13, v58, vcc
	v_mul_f32_e32 v96, 0x41000000, v13
	v_add_f32_e32 v13, 1.0, v15
	v_add_f32_e32 v52, -1.0, v13
	v_sub_f32_e32 v56, v52, v13
	v_add_f32_e32 v56, 1.0, v56
	v_sub_f32_e32 v52, v15, v52
	v_add_f32_e32 v52, v52, v56
	v_frexp_mant_f32_e32 v58, v13
	v_cvt_f64_f32_e32 v[56:57], v13
	v_frexp_exp_i32_f64_e32 v56, v[56:57]
	v_cmp_gt_f32_e32 vcc, s3, v58
	s_nop 1
	v_subbrev_co_u32_e32 v56, vcc, 0, v56, vcc
	v_sub_u32_e32 v57, 0, v56
	v_ldexp_f32 v13, v13, v57
	v_ldexp_f32 v52, v52, v57
	v_add_f32_e32 v57, -1.0, v13
	v_add_f32_e32 v63, 1.0, v13
	v_add_f32_e32 v58, 1.0, v57
	v_add_f32_e32 v67, -1.0, v63
	v_sub_f32_e32 v58, v13, v58
	v_sub_f32_e32 v13, v13, v67
	v_add_f32_e32 v13, v52, v13
	v_add_f32_e32 v58, v52, v58
	v_add_f32_e32 v52, v63, v13
	v_rcp_f32_e32 v67, v52
	v_add_f32_e32 v59, v57, v58
	v_sub_f32_e32 v57, v59, v57
	v_sub_f32_e32 v57, v58, v57
	v_sub_f32_e32 v58, v52, v63
	v_sub_f32_e32 v13, v13, v58
	v_mul_f32_e32 v58, v59, v67
	v_mul_f32_e32 v63, v52, v58
	v_fma_f32 v69, v58, v52, -v63
	v_fmac_f32_e32 v69, v58, v13
	v_add_f32_e32 v70, v63, v69
	v_sub_f32_e32 v71, v59, v70
	v_sub_f32_e32 v59, v59, v71
	v_sub_f32_e32 v63, v70, v63
	v_sub_f32_e32 v59, v59, v70
	v_add_f32_e32 v57, v57, v59
	v_sub_f32_e32 v59, v63, v69
	v_add_f32_e32 v57, v59, v57
	v_add_f32_e32 v59, v71, v57
	v_mul_f32_e32 v63, v67, v59
	v_mul_f32_e32 v69, v52, v63
	v_fma_f32 v52, v63, v52, -v69
	v_fmac_f32_e32 v52, v63, v13
	v_sub_f32_e32 v13, v71, v59
	v_add_f32_e32 v13, v57, v13
	v_add_f32_e32 v57, v69, v52
	v_sub_f32_e32 v70, v59, v57
	v_sub_f32_e32 v59, v59, v70
	v_sub_f32_e32 v69, v57, v69
	v_sub_f32_e32 v57, v59, v57
	v_add_f32_e32 v13, v13, v57
	v_sub_f32_e32 v52, v69, v52
	v_cvt_f32_i32_e32 v56, v56
	v_add_f32_e32 v13, v52, v13
	v_add_f32_e32 v52, v58, v63
	v_add_f32_e32 v13, v70, v13
	v_sub_f32_e32 v57, v52, v58
	v_mul_f32_e32 v13, v67, v13
	v_sub_f32_e32 v57, v63, v57
	v_add_f32_e32 v13, v57, v13
	v_mul_f32_e32 v63, 0x3f317218, v56
	v_add_f32_e32 v57, v52, v13
	v_fma_f32 v67, v56, s10, -v63
	v_mul_f32_e32 v58, v57, v57
	v_fmac_f32_e32 v67, 0xb102e308, v56
; __device__ __forceinline__ void rglru_unit(const Params& p, const WS& ws, int j, int u, bool dry = false) {
;     ...
;   float ba[2][4], bx[2][4], sp[2][4];
; #pragma unroll
;   for (int mt = 0; mt < 2; ++mt)
; #pragma unroll
;     for (int jj = 0; jj < 4; ++jj) {
;       const int ch = j * 1024 + 128 * g + 32 * jq + 16 * mt + 4 * lq + jj;
;       ba[mt][jj] = p.ab_gate_a_b[ch]; bx[mt][jj] = p.ab_gate_x_b[ch];
;       sp[mt][jj] = 8.f * log1pf(__expf(-p.ab_lam[ch]));
;     }
	v_sub_f32_e32 v52, v57, v52
	v_fmamk_f32 v59, v58, 0x3e9b6dac, v192
	v_sub_f32_e32 v13, v13, v52
	v_add_f32_e32 v52, v63, v67
	v_fmaak_f32 v59, v58, v59, 0x3f2aaada
	v_sub_f32_e32 v56, v52, v63
	v_ldexp_f32 v63, v57, 1
	v_mul_f32_e32 v57, v57, v58
	v_mul_f32_e32 v57, v57, v59
	v_add_f32_e32 v58, v63, v57
	v_sub_f32_e32 v59, v58, v63
	v_ldexp_f32 v13, v13, 1
	v_sub_f32_e32 v57, v57, v59
	v_add_f32_e32 v13, v13, v57
	v_add_f32_e32 v57, v58, v13
	v_sub_f32_e32 v58, v57, v58
	v_sub_f32_e32 v13, v13, v58
	v_add_f32_e32 v58, v52, v57
	v_sub_f32_e32 v59, v58, v52
	v_sub_f32_e32 v63, v58, v59
	v_sub_f32_e32 v56, v67, v56
	v_sub_f32_e32 v52, v52, v63
	v_sub_f32_e32 v57, v57, v59
	v_add_f32_e32 v52, v57, v52
	v_add_f32_e32 v57, v56, v13
	v_sub_f32_e32 v59, v57, v56
	v_sub_f32_e32 v63, v57, v59
	v_sub_f32_e32 v56, v56, v63
	v_sub_f32_e32 v13, v13, v59
	v_add_f32_e32 v52, v57, v52
	v_add_f32_e32 v13, v13, v56
	v_add_f32_e32 v56, v58, v52
	v_sub_f32_e32 v57, v56, v58
	v_sub_f32_e32 v52, v52, v57
	v_add_f32_e32 v13, v13, v52
	v_add_f32_e32 v13, v56, v13
	v_cmp_neq_f32_e32 vcc, s21, v15
	v_mul_f32_e32 v52, 0xbfb8aa3b, v53
	v_exp_f32_e32 v56, v52
	v_cndmask_b32_e32 v13, v199, v13, vcc
	v_cmp_ngt_f32_e32 vcc, -1.0, v15
	v_mov_b32_e32 v71, v12
	s_nop 0
	v_cndmask_b32_e32 v13, v200, v13, vcc
	v_cmp_neq_f32_e32 vcc, -1.0, v15
	s_nop 1
	v_cndmask_b32_e32 v13, v194, v13, vcc
	v_cmp_lt_f32_e64 vcc, |v15|, s11
	s_nop 1
	v_cndmask_b32_e32 v13, v13, v15, vcc
	v_mul_f32_e32 v97, 0x41000000, v13
	v_add_f32_e32 v13, 1.0, v56
	v_add_f32_e32 v15, -1.0, v13
	v_sub_f32_e32 v52, v15, v13
	v_add_f32_e32 v52, 1.0, v52
	v_sub_f32_e32 v15, v56, v15
	v_add_f32_e32 v15, v15, v52
	v_frexp_mant_f32_e32 v57, v13
	v_cvt_f64_f32_e32 v[52:53], v13
	v_frexp_exp_i32_f64_e32 v52, v[52:53]
	v_cmp_gt_f32_e32 vcc, s3, v57
	s_nop 1
	v_subbrev_co_u32_e32 v52, vcc, 0, v52, vcc
	v_sub_u32_e32 v53, 0, v52
	v_ldexp_f32 v13, v13, v53
	v_ldexp_f32 v15, v15, v53
	v_add_f32_e32 v53, -1.0, v13
	v_add_f32_e32 v59, 1.0, v13
	v_add_f32_e32 v57, 1.0, v53
	v_add_f32_e32 v63, -1.0, v59
	v_sub_f32_e32 v57, v13, v57
	v_sub_f32_e32 v13, v13, v63
	v_add_f32_e32 v13, v15, v13
	v_add_f32_e32 v57, v15, v57
	v_add_f32_e32 v15, v59, v13
	v_rcp_f32_e32 v63, v15
	v_add_f32_e32 v58, v53, v57
	v_sub_f32_e32 v53, v58, v53
	v_sub_f32_e32 v53, v57, v53
	v_sub_f32_e32 v57, v15, v59
	v_sub_f32_e32 v13, v13, v57
	v_mul_f32_e32 v57, v58, v63
	v_mul_f32_e32 v59, v15, v57
	v_fma_f32 v67, v57, v15, -v59
	v_fmac_f32_e32 v67, v57, v13
	v_add_f32_e32 v69, v59, v67
	v_sub_f32_e32 v70, v58, v69
	v_sub_f32_e32 v58, v58, v70
	v_sub_f32_e32 v59, v69, v59
	v_sub_f32_e32 v58, v58, v69
	v_add_f32_e32 v53, v53, v58
	v_sub_f32_e32 v58, v59, v67
	v_add_f32_e32 v53, v58, v53
	v_add_f32_e32 v58, v70, v53
	v_mul_f32_e32 v59, v63, v58
	v_mul_f32_e32 v67, v15, v59
	v_fma_f32 v15, v59, v15, -v67
	v_fmac_f32_e32 v15, v59, v13
	v_sub_f32_e32 v13, v70, v58
	v_add_f32_e32 v13, v53, v13
	v_add_f32_e32 v53, v67, v15
	v_sub_f32_e32 v69, v58, v53
	v_sub_f32_e32 v58, v58, v69
	v_sub_f32_e32 v67, v53, v67
	v_sub_f32_e32 v53, v58, v53
	v_add_f32_e32 v13, v13, v53
	v_sub_f32_e32 v15, v67, v15
	v_cvt_f32_i32_e32 v52, v52
	v_add_f32_e32 v13, v15, v13
	v_add_f32_e32 v15, v57, v59
	v_add_f32_e32 v13, v69, v13
	v_sub_f32_e32 v53, v15, v57
	v_mul_f32_e32 v13, v63, v13
	v_sub_f32_e32 v53, v59, v53
	v_add_f32_e32 v13, v53, v13
	v_mul_f32_e32 v59, 0x3f317218, v52
	v_add_f32_e32 v53, v15, v13
	v_fma_f32 v63, v52, s10, -v59
	v_mul_f32_e32 v57, v53, v53
	v_fmac_f32_e32 v63, 0xb102e308, v52
	v_sub_f32_e32 v15, v53, v15
	v_fmamk_f32 v58, v57, 0x3e9b6dac, v192
	v_sub_f32_e32 v13, v13, v15
	v_add_f32_e32 v15, v59, v63
	v_fmaak_f32 v58, v57, v58, 0x3f2aaada
	v_sub_f32_e32 v52, v15, v59
	v_ldexp_f32 v59, v53, 1
	v_mul_f32_e32 v53, v53, v57
	v_mul_f32_e32 v53, v53, v58
	v_add_f32_e32 v57, v59, v53
	v_sub_f32_e32 v58, v57, v59
	v_ldexp_f32 v13, v13, 1
	v_sub_f32_e32 v53, v53, v58
	v_add_f32_e32 v13, v13, v53
	v_add_f32_e32 v53, v57, v13
	v_sub_f32_e32 v57, v53, v57
	v_sub_f32_e32 v13, v13, v57
	v_add_f32_e32 v57, v15, v53
	v_sub_f32_e32 v58, v57, v15
	v_sub_f32_e32 v59, v57, v58
	v_sub_f32_e32 v52, v63, v52
	v_sub_f32_e32 v15, v15, v59
	v_sub_f32_e32 v53, v53, v58
	v_add_f32_e32 v15, v53, v15
	v_add_f32_e32 v53, v52, v13
	v_sub_f32_e32 v58, v53, v52
	v_sub_f32_e32 v59, v53, v58
	v_sub_f32_e32 v52, v52, v59
	v_sub_f32_e32 v13, v13, v58
	v_add_f32_e32 v15, v53, v15
	v_add_f32_e32 v13, v13, v52
	v_add_f32_e32 v52, v57, v15
	v_sub_f32_e32 v53, v52, v57
	v_sub_f32_e32 v15, v15, v53
	v_add_f32_e32 v13, v13, v15
	v_add_f32_e32 v13, v52, v13
	v_cmp_neq_f32_e32 vcc, s21, v56
	v_mul_f32_e32 v15, 0xbfb8aa3b, v54
	v_exp_f32_e32 v15, v15
	v_cndmask_b32_e32 v13, v199, v13, vcc
	v_cmp_ngt_f32_e32 vcc, -1.0, v56
	v_lshlrev_b32_e32 v70, 1, v14
	s_nop 0
	v_cndmask_b32_e32 v13, v200, v13, vcc
	v_cmp_neq_f32_e32 vcc, -1.0, v56
	s_nop 1
	v_cndmask_b32_e32 v13, v194, v13, vcc
	v_cmp_lt_f32_e64 vcc, |v56|, s11
	s_nop 1
	v_cndmask_b32_e32 v13, v13, v56, vcc
	v_mul_f32_e32 v98, 0x41000000, v13
	v_add_f32_e32 v13, 1.0, v15
	v_add_f32_e32 v52, -1.0, v13
	v_sub_f32_e32 v53, v52, v13
	v_add_f32_e32 v53, 1.0, v53
	v_sub_f32_e32 v52, v15, v52
	v_add_f32_e32 v54, v52, v53
	v_frexp_mant_f32_e32 v56, v13
	v_cvt_f64_f32_e32 v[52:53], v13
	v_frexp_exp_i32_f64_e32 v52, v[52:53]
	v_cmp_gt_f32_e32 vcc, s3, v56
	s_nop 1
	v_subbrev_co_u32_e32 v52, vcc, 0, v52, vcc
	v_sub_u32_e32 v53, 0, v52
	v_ldexp_f32 v13, v13, v53
	v_ldexp_f32 v53, v54, v53
	v_add_f32_e32 v54, -1.0, v13
	v_add_f32_e32 v58, 1.0, v13
	v_add_f32_e32 v56, 1.0, v54
	v_add_f32_e32 v59, -1.0, v58
	v_sub_f32_e32 v56, v13, v56
	v_sub_f32_e32 v13, v13, v59
; __device__ __forceinline__ void rglru_unit(const Params& p, const WS& ws, int j, int u, bool dry = false) {
;     ...
;   float ba[2][4], bx[2][4], sp[2][4];
; #pragma unroll
;   for (int mt = 0; mt < 2; ++mt)
; #pragma unroll
;     for (int jj = 0; jj < 4; ++jj) {
;       const int ch = j * 1024 + 128 * g + 32 * jq + 16 * mt + 4 * lq + jj;
;       ba[mt][jj] = p.ab_gate_a_b[ch]; bx[mt][jj] = p.ab_gate_x_b[ch];
;       sp[mt][jj] = 8.f * log1pf(__expf(-p.ab_lam[ch]));
;     }
	v_add_f32_e32 v13, v53, v13
	v_add_f32_e32 v56, v53, v56
	v_add_f32_e32 v53, v58, v13
	v_rcp_f32_e32 v59, v53
	v_add_f32_e32 v57, v54, v56
	v_sub_f32_e32 v54, v57, v54
	v_sub_f32_e32 v54, v56, v54
	v_sub_f32_e32 v56, v53, v58
	v_sub_f32_e32 v13, v13, v56
	v_mul_f32_e32 v56, v57, v59
	v_mul_f32_e32 v58, v53, v56
	v_fma_f32 v63, v56, v53, -v58
	v_fmac_f32_e32 v63, v56, v13
	v_add_f32_e32 v67, v58, v63
	v_sub_f32_e32 v69, v57, v67
	v_sub_f32_e32 v57, v57, v69
	v_sub_f32_e32 v58, v67, v58
	v_sub_f32_e32 v57, v57, v67
	v_add_f32_e32 v54, v54, v57
	v_sub_f32_e32 v57, v58, v63
	v_add_f32_e32 v54, v57, v54
	v_add_f32_e32 v57, v69, v54
	v_mul_f32_e32 v58, v59, v57
	v_mul_f32_e32 v63, v53, v58
	v_fma_f32 v53, v58, v53, -v63
	v_fmac_f32_e32 v53, v58, v13
	v_sub_f32_e32 v13, v69, v57
	v_add_f32_e32 v13, v54, v13
	v_add_f32_e32 v54, v63, v53
	v_sub_f32_e32 v67, v57, v54
	v_sub_f32_e32 v57, v57, v67
	v_sub_f32_e32 v63, v54, v63
	v_sub_f32_e32 v54, v57, v54
	v_add_f32_e32 v13, v13, v54
	v_sub_f32_e32 v53, v63, v53
	v_cvt_f32_i32_e32 v52, v52
	v_add_f32_e32 v13, v53, v13
	v_add_f32_e32 v53, v56, v58
	v_add_f32_e32 v13, v67, v13
	v_sub_f32_e32 v54, v53, v56
	v_mul_f32_e32 v13, v59, v13
	v_sub_f32_e32 v54, v58, v54
	v_add_f32_e32 v13, v54, v13
	v_mul_f32_e32 v58, 0x3f317218, v52
	v_add_f32_e32 v54, v53, v13
	v_fma_f32 v59, v52, s10, -v58
	v_mul_f32_e32 v56, v54, v54
	v_fmac_f32_e32 v59, 0xb102e308, v52
	v_sub_f32_e32 v52, v54, v53
	v_fmamk_f32 v57, v56, 0x3e9b6dac, v192
	v_sub_f32_e32 v13, v13, v52
	v_add_f32_e32 v52, v58, v59
	v_fmaak_f32 v57, v56, v57, 0x3f2aaada
	v_sub_f32_e32 v53, v52, v58
	v_ldexp_f32 v58, v54, 1
	v_mul_f32_e32 v54, v54, v56
	v_mul_f32_e32 v54, v54, v57
	v_add_f32_e32 v56, v58, v54
	v_sub_f32_e32 v57, v56, v58
	v_ldexp_f32 v13, v13, 1
	v_sub_f32_e32 v54, v54, v57
	v_add_f32_e32 v13, v13, v54
	v_add_f32_e32 v54, v56, v13
	v_sub_f32_e32 v56, v54, v56
	v_sub_f32_e32 v13, v13, v56
	v_add_f32_e32 v56, v52, v54
	v_sub_f32_e32 v57, v56, v52
	v_sub_f32_e32 v58, v56, v57
	v_sub_f32_e32 v53, v59, v53
	v_sub_f32_e32 v52, v52, v58
	v_sub_f32_e32 v54, v54, v57
	v_add_f32_e32 v52, v54, v52
	v_add_f32_e32 v54, v53, v13
	v_sub_f32_e32 v57, v54, v53
	v_sub_f32_e32 v58, v54, v57
	v_sub_f32_e32 v53, v53, v58
	v_sub_f32_e32 v13, v13, v57
	v_add_f32_e32 v52, v54, v52
	v_add_f32_e32 v13, v13, v53
	v_add_f32_e32 v53, v56, v52
	v_sub_f32_e32 v54, v53, v56
	v_sub_f32_e32 v52, v52, v54
	v_add_f32_e32 v13, v13, v52
	v_add_f32_e32 v13, v53, v13
	v_cmp_neq_f32_e32 vcc, s21, v15
	v_mul_f32_e32 v52, 0xbfb8aa3b, v55
	v_exp_f32_e32 v54, v52
	v_cndmask_b32_e32 v13, v199, v13, vcc
	v_cmp_ngt_f32_e32 vcc, -1.0, v15
	v_mov_b32_e32 v69, v12
	s_nop 0
	v_cndmask_b32_e32 v13, v200, v13, vcc
	v_cmp_neq_f32_e32 vcc, -1.0, v15
	s_nop 1
	v_cndmask_b32_e32 v13, v194, v13, vcc
	v_cmp_lt_f32_e64 vcc, |v15|, s11
	s_nop 1
	v_cndmask_b32_e32 v13, v13, v15, vcc
	v_mul_f32_e32 v99, 0x41000000, v13
	v_add_f32_e32 v13, 1.0, v54
	v_add_f32_e32 v15, -1.0, v13
	v_sub_f32_e32 v52, v15, v13
	v_add_f32_e32 v52, 1.0, v52
	v_sub_f32_e32 v15, v54, v15
	v_add_f32_e32 v15, v15, v52
	v_frexp_mant_f32_e32 v55, v13
	v_cvt_f64_f32_e32 v[52:53], v13
	v_frexp_exp_i32_f64_e32 v52, v[52:53]
	v_cmp_gt_f32_e32 vcc, s3, v55
	s_nop 1
	v_subbrev_co_u32_e32 v52, vcc, 0, v52, vcc
	v_sub_u32_e32 v53, 0, v52
	v_ldexp_f32 v13, v13, v53
	v_ldexp_f32 v15, v15, v53
	v_add_f32_e32 v53, -1.0, v13
	v_add_f32_e32 v57, 1.0, v13
	v_add_f32_e32 v55, 1.0, v53
	v_add_f32_e32 v58, -1.0, v57
	v_sub_f32_e32 v55, v13, v55
	v_sub_f32_e32 v13, v13, v58
	v_add_f32_e32 v13, v15, v13
	v_add_f32_e32 v55, v15, v55
	v_add_f32_e32 v15, v57, v13
	v_rcp_f32_e32 v58, v15
	v_add_f32_e32 v56, v53, v55
	v_sub_f32_e32 v53, v56, v53
	v_sub_f32_e32 v53, v55, v53
	v_sub_f32_e32 v55, v15, v57
; __device__ __forceinline__ void rglru_unit(const Params& p, const WS& ws, int j, int u, bool dry = false) {
;     ...
;   float ba[2][4], bx[2][4], sp[2][4];
; #pragma unroll
;   for (int mt = 0; mt < 2; ++mt)
; #pragma unroll
;     for (int jj = 0; jj < 4; ++jj) {
;       const int ch = j * 1024 + 128 * g + 32 * jq + 16 * mt + 4 * lq + jj;
;       ba[mt][jj] = p.ab_gate_a_b[ch]; bx[mt][jj] = p.ab_gate_x_b[ch];
;       sp[mt][jj] = 8.f * log1pf(__expf(-p.ab_lam[ch]));
;     }
;   const int sc = tid & 31, ssg = tid >> 5;
;   u32x4 xinA[4], xinB[4];
;   bf16_t gavA[8], gavB[8];
;   auto prefetch = [&](int tile, u32x4 (&xin)[4], bf16_t (&gav)[8]) {
;     const int t0 = 64 * tile;
; #pragma unroll
;     for (int i = 0; i < 4; ++i) {
;       const int ci = tid + 256 * i; const int row = ci >> 4, ch = ci & 15; const int t = t0 + row;
;       xin[i] = (u32x4){0, 0, 0, 0};
;       if (t < T_) xin[i] = *(const u32x4*)(ws.XA + (size_t)(b * T_ + t) * 1024 + 128 * g + 8 * ch);
;     }
; #pragma unroll
;     for (int i = 0; i < 8; ++i) {
;       const int t = t0 + 8 * ssg + i;
;       gav[i] = 0;
;       if (t < T_) gav[i] = ws.GA[(size_t)(b * T_ + t) * 1024 + 128 * g + 32 * jq + sc];
;     }
;   };
;   prefetch(0, xinA, gavA);
;   prefetch(1, xinB, gavB);
;   __syncthreads();
	v_sub_f32_e32 v13, v13, v55
	v_mul_f32_e32 v55, v56, v58
	v_mul_f32_e32 v57, v15, v55
	v_fma_f32 v59, v55, v15, -v57
	v_fmac_f32_e32 v59, v55, v13
	v_add_f32_e32 v63, v57, v59
	v_sub_f32_e32 v67, v56, v63
	v_sub_f32_e32 v56, v56, v67
	v_sub_f32_e32 v57, v63, v57
	v_sub_f32_e32 v56, v56, v63
	v_add_f32_e32 v53, v53, v56
	v_sub_f32_e32 v56, v57, v59
	v_add_f32_e32 v53, v56, v53
	v_add_f32_e32 v56, v67, v53
	v_mul_f32_e32 v57, v58, v56
	v_mul_f32_e32 v59, v15, v57
	v_fma_f32 v15, v57, v15, -v59
	v_fmac_f32_e32 v15, v57, v13
	v_sub_f32_e32 v13, v67, v56
	v_add_f32_e32 v13, v53, v13
	v_add_f32_e32 v53, v59, v15
	v_sub_f32_e32 v63, v56, v53
	v_sub_f32_e32 v56, v56, v63
	v_sub_f32_e32 v59, v53, v59
	v_sub_f32_e32 v53, v56, v53
	v_add_f32_e32 v13, v13, v53
	v_sub_f32_e32 v15, v59, v15
	v_cvt_f32_i32_e32 v52, v52
	v_add_f32_e32 v13, v15, v13
	v_add_f32_e32 v15, v55, v57
	v_add_f32_e32 v13, v63, v13
	v_sub_f32_e32 v53, v15, v55
	v_mul_f32_e32 v13, v58, v13
	v_sub_f32_e32 v53, v57, v53
	v_add_f32_e32 v13, v53, v13
	v_mul_f32_e32 v57, 0x3f317218, v52
	v_add_f32_e32 v53, v15, v13
	v_fma_f32 v58, v52, s10, -v57
	v_mul_f32_e32 v55, v53, v53
	v_fmac_f32_e32 v58, 0xb102e308, v52
	v_sub_f32_e32 v15, v53, v15
	v_fmamk_f32 v56, v55, 0x3e9b6dac, v192
	v_sub_f32_e32 v13, v13, v15
	v_add_f32_e32 v15, v57, v58
	v_fmaak_f32 v56, v55, v56, 0x3f2aaada
	v_sub_f32_e32 v52, v15, v57
	v_ldexp_f32 v57, v53, 1
	v_mul_f32_e32 v53, v53, v55
	v_mul_f32_e32 v53, v53, v56
	v_add_f32_e32 v55, v57, v53
	v_sub_f32_e32 v56, v55, v57
	v_ldexp_f32 v13, v13, 1
	v_sub_f32_e32 v53, v53, v56
	v_add_f32_e32 v13, v13, v53
	v_add_f32_e32 v53, v55, v13
	v_sub_f32_e32 v55, v53, v55
	v_sub_f32_e32 v13, v13, v55
	v_add_f32_e32 v55, v15, v53
	v_sub_f32_e32 v56, v55, v15
	v_sub_f32_e32 v57, v55, v56
	v_sub_f32_e32 v52, v58, v52
	v_sub_f32_e32 v15, v15, v57
	v_sub_f32_e32 v53, v53, v56
	v_add_f32_e32 v15, v53, v15
	v_add_f32_e32 v53, v52, v13
	v_sub_f32_e32 v56, v53, v52
	v_sub_f32_e32 v57, v53, v56
	v_sub_f32_e32 v52, v52, v57
	v_sub_f32_e32 v13, v13, v56
	v_add_f32_e32 v15, v53, v15
	v_add_f32_e32 v13, v13, v52
	v_add_f32_e32 v52, v55, v15
	v_sub_f32_e32 v53, v52, v55
	v_sub_f32_e32 v15, v15, v53
	v_add_f32_e32 v13, v13, v15
	v_mul_lo_u32 v15, v79, s19
	v_add3_u32 v106, s8, v15, v62
	v_mul_lo_u32 v15, v80, s19
	v_add3_u32 v107, s8, v15, v62
	v_mul_lo_u32 v15, v81, s19
	v_add_f32_e32 v13, v52, v13
	v_cmp_neq_f32_e32 vcc, s21, v54
	v_add3_u32 v109, s8, v15, v62
	v_mul_lo_u32 v15, v82, s19
	v_cndmask_b32_e32 v13, v199, v13, vcc
	v_cmp_ngt_f32_e32 vcc, -1.0, v54
	v_add3_u32 v110, s8, v15, v62
	v_ashrrev_i32_e32 v15, 2, v61
	v_cndmask_b32_e32 v13, v200, v13, vcc
	v_cmp_neq_f32_e32 vcc, -1.0, v54
	v_bfi_b32 v15, -16, v15, v61
	v_mul_lo_u32 v52, v15, s19
	v_cndmask_b32_e32 v13, v194, v13, vcc
	v_cmp_lt_f32_e64 vcc, |v54|, s11
	v_add_u32_e32 v53, s8, v52
	v_lshlrev_b32_e32 v52, 4, v64
	v_cndmask_b32_e32 v13, v13, v54, vcc
	v_mul_f32_e32 v105, 0x41000000, v13
	v_and_b32_e32 v13, 15, v61
	v_add_u32_e32 v111, v53, v52
	v_add_u32_e32 v52, s8, v52
	v_mul_u32_u24_e32 v13, 0x88, v13
	v_mad_u64_u32 v[72:73], s[10:11], v15, s9, v[52:53]
	v_lshl_add_u64 v[14:15], s[54:55], 0, v[70:71]
	v_lshl_add_u32 v112, v13, 1, v52
	v_lshlrev_b32_e32 v13, 1, v65
	s_movk_i32 s9, 0x108
	v_lshl_add_u64 v[14:15], v[14:15], 0, s[92:93]
	v_add3_u32 v113, v53, s92, v13
	v_mad_u64_u32 v[52:53], s[10:11], v66, s9, v[60:61]
	v_lshl_add_u64 v[74:75], v[14:15], 0, v[68:69]
	v_lshl_add_u64 v[14:15], s[4:5], 0, v[70:71]
	v_mov_b32_e32 v63, v12
	v_lshl_add_u32 v114, v52, 2, s8
	v_cmp_lt_i32_e32 vcc, 0, v66
	v_or_b32_e32 v73, 7, v84
	v_lshl_add_u64 v[76:77], v[14:15], 0, v[62:63]
	v_add_u32_e32 v69, v84, v83
	v_add_u32_e32 v71, v82, v84
	s_mov_b32 s4, -1
	.p2align 6

; __device__ __forceinline__ int opaque_tid() { int t = threadIdx.x & 255; asm volatile("" : "+v"(t)); return t; }
; #define smem (smem_all + half_id() * SMEM_BYTES)
; __device__ __forceinline__ void gla_unit(const Params& p, const WS& ws, int u, bool dry = false) {
;   const int sl = u & 7; const int bh = u >> 3; const int hd = bh & 3, b = bh >> 2;
;   bf16_t* QDs = (bf16_t*)smem;
;   bf16_t* KIs = QDs + 64 * 136;
;   bf16_t* KIT = KIs + 64 * 136;
;   bf16_t* VTs = KIT + 128 * 72;
;   bf16_t* STs = VTs + 32 * 72;
;   bf16_t* Ps = STs + 32 * 136;
;   const int tid = opaque_tid(), lane = tid & 63, w = tid >> 6, lr = lane & 15, lq = lane >> 4;
;   for (int i = tid; i < 32 * 136 / 2; i += 256) ((unsigned*)STs)[i] = 0u;
;   f32x4 sacc[2][2];
; #pragma unroll
;   for (int a = 0; a < 2; ++a)
; #pragma unroll
;     for (int bb = 0; bb < 2; ++bb) sacc[a][bb] = (f32x4){0.f, 0.f, 0.f, 0.f};
;   u32x4 qrA[4], krA[4], vrA, qrB[4], krB[4], vrB;
;   float eblA[2], eblB[2];
;   const float* BLp = ws.BL + (size_t)((b * 4 + hd) * 33) * 128;
;   auto prefetch = [&](int c, u32x4 (&qr)[4], u32x4 (&kr)[4], u32x4& vr, float (&ebl)[2]) {
;     const int tbase = 64 * c - 48;
; #pragma unroll
;     for (int i = 0; i < 4; ++i) {
;       const int ci = tid + 256 * i; const int row = ci >> 4, ch = ci & 15; const int t = tbase + row;
;       qr[i] = (u32x4){0, 0, 0, 0}; kr[i] = (u32x4){0, 0, 0, 0};
;       if (t >= 0) {
;         qr[i] = *(const u32x4*)(ws.Q + (size_t)(b * T_ + t) * 512 + hd * 128 + ch * 8);
;         kr[i] = *(const u32x4*)(ws.K + (size_t)(b * T_ + t) * 512 + hd * 128 + ch * 8);
;       }
;     }
;     {
;       const int row = tid >> 2, ch = tid & 3; const int t = tbase + row;
;       vr = (u32x4){0, 0, 0, 0};
;       if (t >= 0) vr = *(const u32x4*)(ws.V + (size_t)(b * T_ + t) * 1024 + hd * 256 + sl * 32 + ch * 8);
;     }
;     ebl[0] = BLp[c * 128 + 16 * (2 * w) + lr];
;     ebl[1] = BLp[c * 128 + 16 * (2 * w + 1) + lr];
;   };
;   prefetch(0, qrA, krA, vrA, eblA);
;   prefetch(1, qrB, krB, vrB, eblB);
;   __syncthreads();
;   u32x2 opend[2]; float sqpend = 0.f; int tpend = -1;
;   opend[0] = (u32x2){0u, 0u}; opend[1] = (u32x2){0u, 0u};
.LBB0_1606:
	s_or_b64 exec, exec, s[4:5]
	global_load_dword v204, v[6:7], off offset:512
	global_load_dword v179, v[6:7], off offset:576
	v_and_b32_e32 v14, 0x78, v11
	v_mul_lo_u32 v7, v131, s19
	v_lshlrev_b32_e32 v6, 1, v14
	v_mul_u32_u24_e32 v14, 0x48, v14
	v_add3_u32 v147, s37, v7, v6
	v_bitop3_b32 v7, v11, v131, 56 bitop3:0x6c
	v_lshlrev_b32_e32 v14, 1, v14
	v_add_u32_e32 v86, s37, v14
	v_lshlrev_b32_e32 v7, 1, v7
	v_add_u32_e32 v148, v86, v7
	v_add3_u32 v149, s37, v7, v14
	v_mul_lo_u32 v7, v142, s19
	v_add3_u32 v150, s37, v7, v6
	v_bitop3_b32 v7, v11, v142, 56 bitop3:0x6c
	v_lshlrev_b32_e32 v7, 1, v7
	v_add_u32_e32 v151, v86, v7
	v_add3_u32 v152, s37, v7, v14
	v_mul_lo_u32 v7, v143, s19
	v_add3_u32 v153, s37, v7, v6
	v_bitop3_b32 v7, v11, v143, 56 bitop3:0x6c
	v_lshlrev_b32_e32 v7, 1, v7
	v_add_u32_e32 v154, v86, v7
	v_add3_u32 v155, s37, v7, v14
	v_mul_lo_u32 v7, v144, s19
	v_add3_u32 v156, s37, v7, v6
	v_bitop3_b32 v7, v11, v144, 56 bitop3:0x6c
	v_lshlrev_b32_e32 v7, 1, v7
	v_add_u32_e32 v157, v86, v7
	v_add3_u32 v158, s37, v7, v14
	v_xor_b32_e32 v7, v8, v145
	v_mul_u32_u24_e32 v11, 0x48, v8
	v_bfe_u32 v15, v84, 4, 2
	v_lshlrev_b32_e32 v11, 1, v11
	v_lshlrev_b32_e32 v7, 1, v7
	v_add3_u32 v159, s37, v11, v7
	v_add3_u32 v160, s37, v7, v11
	v_lshlrev_b32_e32 v7, 4, v15
	v_lshl_or_b32 v161, v85, 4, v10
	v_add_u32_e32 v86, s37, v7
	v_mad_u64_u32 v[128:129], s[6:7], v161, s19, v[86:87]
	v_cmp_lt_i32_e32 vcc, -1, v85
	v_cmp_lt_i32_e64 s[38:39], 0, v85
	v_cmp_lt_i32_e64 s[40:41], 1, v85
	v_cmp_lt_i32_e64 s[42:43], 2, v85
	v_mul_u32_u24_e32 v85, 0x88, v10
	v_lshl_add_u32 v129, v85, 1, v86
	v_and_b32_e32 v86, 64, v191
	v_xor_b32_e32 v85, 16, v191
	v_add_u32_e32 v86, 64, v86
	v_cmp_lt_i32_e64 s[44:45], v85, v86
	s_movk_i32 s3, 0x90
	v_lshlrev_b32_e32 v14, 3, v15
	v_cndmask_b32_e64 v85, v191, v85, s[44:45]
	v_lshlrev_b32_e32 v163, 2, v85
	v_xor_b32_e32 v85, 32, v191
	v_cmp_lt_i32_e64 s[44:45], v85, v86
	v_bitop3_b32 v88, v4, v14, 40 bitop3:0x6c
	v_or_b32_e32 v13, 16, v10
	v_cndmask_b32_e64 v85, v191, v85, s[44:45]
	v_lshlrev_b32_e32 v168, 2, v85
	v_mul_lo_u32 v85, v4, s3
	v_add_u32_e32 v85, s37, v85
	v_lshl_add_u32 v169, v88, 1, v85
	v_mov_b32_e32 v88, s37
	v_mad_u32_u24 v88, v10, s3, v88
	v_bitop3_b32 v90, v10, 24, 16 bitop3:0xc8
	v_lshlrev_b32_e32 v130, 2, v15
	v_lshlrev_b32_e32 v10, 7, v10
	v_add3_u32 v176, v88, v10, v7
	v_or_b32_e32 v10, 16, v130
	v_cmp_gt_i32_e64 s[54:55], v10, v161
	v_cmp_lt_i32_e64 s[56:57], v10, v161
	v_or_b32_e32 v10, 18, v130
	v_cmp_gt_i32_e64 s[58:59], v10, v161
	v_or_b32_e32 v10, 19, v130
	v_cmp_gt_i32_e64 s[60:61], v10, v161
	v_or_b32_e32 v10, 32, v130
	v_cmp_gt_i32_e64 s[62:63], v10, v161
	v_cmp_lt_i32_e64 s[64:65], v10, v161
	v_or_b32_e32 v10, 34, v130
	v_cmp_gt_i32_e64 s[66:67], v10, v161
	v_or_b32_e32 v10, 35, v130
	s_add_u32 s4, s8, 0xe445000
	v_cmp_gt_i32_e64 s[68:69], v10, v161
	v_or_b32_e32 v10, 48, v130
	s_addc_u32 s5, s9, 0
	s_add_i32 s36, s37, 0x10400
	v_mul_lo_u32 v87, v161, s3
	v_cmp_gt_i32_e64 s[70:71], v10, v161
	v_cmp_lt_i32_e64 s[72:73], v10, v161
	v_or_b32_e32 v10, 50, v130
	v_add_u32_e32 v87, s36, v87
	v_cmp_gt_i32_e64 s[74:75], v10, v161
	v_or_b32_e32 v10, 51, v130
	v_cmp_gt_i32_e64 s[76:77], v10, v161
	v_add_u32_e32 v177, v87, v7
	v_mul_u32_u24_e32 v7, 0x440, v15
	v_lshlrev_b32_e32 v10, 1, v4
	s_lshl_b32 s36, s10, 3
	v_add3_u32 v178, s37, v7, v10
	v_or_b32_e32 v7, 16, v4
	s_lshl_b32 s6, s10, 5
	v_mul_lo_u32 v10, v7, s3
	s_add_u32 s6, s4, s6
	v_and_b32_e32 v89, 8, v84
	v_bitop3_b32 v84, v14, v84, 8 bitop3:0x78
	v_add_u32_e32 v10, s37, v10
	s_addc_u32 s7, s5, 0
	s_lshl_b32 s37, s34, 2
	v_lshl_add_u32 v170, v84, 1, v88
	v_add_u32_e32 v84, 0x900, v88
	v_bitop3_b32 v13, v14, v13, 24 bitop3:0x78
	s_add_u32 s6, s6, s37
	v_lshl_add_u32 v171, v13, 1, v84
	v_or_b32_e32 v13, 32, v14
	s_addc_u32 s7, s7, 0
	s_lshl_b32 s37, s10, 8
	v_cmp_eq_u32_e64 s[44:45], 0, v15
	v_bitop3_b32 v15, v7, v14, 56 bitop3:0x6c
	v_bitop3_b32 v7, v7, v13, 56 bitop3:0x6c
	s_add_u32 s12, s12, s37
	v_and_b32_e32 v86, 40, v4
	v_lshl_add_u32 v181, v7, 1, v10
	s_addc_u32 s13, s13, 0
	v_mov_b32_e32 v7, v12
	v_bitop3_b32 v86, v14, v86, 32 bitop3:0x36
	v_lshl_add_u64 v[132:133], s[12:13], 0, v[6:7]
	s_add_u32 s12, s80, s37
	s_mulk_i32 s11, 0x84
	s_mul_i32 s10, s10, 33
	v_lshl_add_u32 v172, v86, 1, v85
	v_bitop3_b32 v85, v14, v89, 32 bitop3:0x36
	s_addc_u32 s13, s81, 0
	s_add_i32 s10, s11, s10
	v_lshl_add_u32 v173, v85, 1, v88
	v_bitop3_b32 v85, v14, v90, 32 bitop3:0x36
	s_ashr_i32 s11, s10, 31
	v_lshl_add_u32 v174, v85, 1, v84
	v_or_b32_e32 v84, 2, v130
	s_lshl_b64 s[10:11], s[10:11], 9
	v_cmp_gt_i32_e64 s[50:51], v84, v161
	v_or_b32_e32 v84, 3, v130
	s_add_u32 s8, s8, s10
	v_cmp_gt_i32_e64 s[52:53], v84, v161
	v_lshl_add_u64 v[84:85], v[126:127], 1, s[96:97]
	s_addc_u32 s9, s9, s11
	v_subrev_u32_e32 v162, 48, v161
	v_lshl_add_u32 v180, v15, 1, v10
	v_lshl_add_u64 v[84:85], v[124:125], 1, v[84:85]
	v_mov_b32_e32 v15, v12
	v_lshl_add_u64 v[4:5], v[4:5], 2, s[8:9]
	s_mov_b64 s[8:9], 0xe649400
	v_mov_b32_e32 v10, 0
	s_mov_b32 s35, 1
	v_mov_b32_e32 v11, -1
	s_mov_b32 s92, 0
	v_cmp_gt_i32_e64 s[46:47], v130, v161
	v_cmp_lt_i32_e64 s[48:49], v130, v161
	v_add_u32_e32 v182, v87, v14
	v_lshl_add_u64 v[134:135], s[12:13], 0, v[6:7]
	v_lshl_add_u64 v[136:137], v[8:9], 1, v[84:85]
	v_lshl_add_u64 v[138:139], v[84:85], 0, v[14:15]
	v_lshl_add_u64 v[140:141], v[4:5], 0, s[8:9]
	v_add_u32_e32 v183, v145, v146
	v_add_u32_e32 v184, v144, v146
	v_add_u32_e32 v185, v143, v146
	v_add_u32_e32 v201, v142, v146
	v_add_u32_e32 v202, v131, v146
	v_add_u32_e32 v203, v162, v146
	v_mov_b32_e32 v4, 0
	v_mov_b32_e32 v5, 0
	v_mov_b32_e32 v6, 0
	v_mov_b32_e32 v7, 0
	s_mov_b32 s37, 0
	v_mov_b32_e32 v92, 0
	v_mov_b32_e32 v93, v10
	v_mov_b32_e32 v94, v10
	v_mov_b32_e32 v95, v10
	v_mov_b32_e32 v96, 0
	v_mov_b32_e32 v97, v10
	v_mov_b32_e32 v98, v10
	v_mov_b32_e32 v99, v10
	v_mov_b32_e32 v88, 0
	v_mov_b32_e32 v89, v10
	v_mov_b32_e32 v90, v10
	v_mov_b32_e32 v91, v10
	v_mov_b32_e32 v84, 0
	v_mov_b32_e32 v85, v10
	v_mov_b32_e32 v86, v10
	v_mov_b32_e32 v87, v10
	s_waitcnt lgkmcnt(0)
	s_barrier
	.p2align 6

;     ...
; #pragma unroll 1
;     for (int s = 0; s < S; s += 2) {
;       issue(ra0, rb0, rx0);
;       compute(0);
;       store(ra1, rb1, rx1, 1);
;       __syncthreads();
;       issue(ra1, rb1, rx1);
;       compute(1);
;       c_kt += 2;
;       if (c_kt == nk) { c_kt = 0; tile_end(); }
;       store(ra0, rb0, rx0, 0);
;       __syncthreads();
;     }
.LBB0_1779:
	s_or_b64 exec, exec, s[4:5]
	s_load_dwordx2 s[4:5], s[0:1], 0x110
	s_add_i32 s58, s58, 1
	s_cmp_eq_u32 s58, 32
	s_cselect_b32 s6, 0, s58
	s_waitcnt lgkmcnt(0)
	s_cselect_b32 s4, s4, 0
	s_add_i32 s7, s4, s57
	s_add_i32 s56, s56, 2
	s_cmp_lt_i32 s56, s31
	s_barrier
	s_cbranch_scc0 .LBB0_1824
	.p2align 6
